# attention: -m broadcast before the first LDS wait, K LDS-DMA (saddr form) after the first QK MFMA pair, V LDS-DMA after the first PV MFMA group
# speedup vs baseline: 1.0255x; 1.0031x over previous
; #define SBAR() __builtin_amdgcn_sched_barrier(0)
; #define KRD(A, B, d0) do { const int ad_ = (kc ^ ((d0) << 5)) + kbt; A = lds_rd128<0>(ad_); B = lds_rd128<8192>(ad_); } while (0)
; #define KW(N) do { asm volatile("s_waitcnt lgkmcnt(" #N ")" ::: "memory"); SBAR(); } while (0)
; __device__ __forceinline__ void qkt_pipe(f32x16& p0, f32x16& p1, int kbt, int kc, const bf16x8* qr, const f32x16& z) {
;   bf16x8 a0, b0, a1, b1, a2, b2, a3, b3;
;     ...
;   KRD(a0, b0, 0); KRD(a1, b1, 1); KRD(a2, b2, 2); KRD(a3, b3, 3);
;   KW(6); p0 = __builtin_amdgcn_mfma_f32_32x32x16_bf16(a0, qr[0], z, 0, 0, 0);  p1 = __builtin_amdgcn_mfma_f32_32x32x16_bf16(b0, qr[0], z, 0, 0, 0);  SBAR(); KRD(a0, b0, 4);
;   KW(6); p0 = __builtin_amdgcn_mfma_f32_32x32x16_bf16(a1, qr[1], p0, 0, 0, 0); p1 = __builtin_amdgcn_mfma_f32_32x32x16_bf16(b1, qr[1], p1, 0, 0, 0); SBAR(); KRD(a1, b1, 5);
;   KW(6); p0 = __builtin_amdgcn_mfma_f32_32x32x16_bf16(a2, qr[2], p0, 0, 0, 0); p1 = __builtin_amdgcn_mfma_f32_32x32x16_bf16(b2, qr[2], p1, 0, 0, 0); SBAR(); KRD(a2, b2, 6);
;   KW(6); p0 = __builtin_amdgcn_mfma_f32_32x32x16_bf16(a3, qr[3], p0, 0, 0, 0); p1 = __builtin_amdgcn_mfma_f32_32x32x16_bf16(b3, qr[3], p1, 0, 0, 0); SBAR(); KRD(a3, b3, 7);
;   KW(6); p0 = __builtin_amdgcn_mfma_f32_32x32x16_bf16(a0, qr[4], p0, 0, 0, 0); p1 = __builtin_amdgcn_mfma_f32_32x32x16_bf16(b0, qr[4], p1, 0, 0, 0); SBAR();
;   KW(4); p0 = __builtin_amdgcn_mfma_f32_32x32x16_bf16(a1, qr[5], p0, 0, 0, 0); p1 = __builtin_amdgcn_mfma_f32_32x32x16_bf16(b1, qr[5], p1, 0, 0, 0); SBAR();
;   KW(2); p0 = __builtin_amdgcn_mfma_f32_32x32x16_bf16(a2, qr[6], p0, 0, 0, 0); p1 = __builtin_amdgcn_mfma_f32_32x32x16_bf16(b2, qr[6], p1, 0, 0, 0); SBAR();
;   KW(0); p0 = __builtin_amdgcn_mfma_f32_32x32x16_bf16(a3, qr[7], p0, 0, 0, 0); p1 = __builtin_amdgcn_mfma_f32_32x32x16_bf16(b3, qr[7], p1, 0, 0, 0);
; template <int mode> ...
;     ...
;   for (int j = 0; j < NT; ++j) {
;     const bool more = j + 2 < NT;
;     if (more) DMA_K(j + 2, s2);
;     f32x16 p0, p1; bf16x8 pa0, pa1, pa2, pa3;
;     __builtin_amdgcn_s_setprio(2);
;     { f32x16 negm;
; #pragma unroll
;       for (int r = 0; r < 16; ++r) negm[r] = -m_reg;
;       qkt_pipe(p0, p1, kb0 + s0 * 16384, kc, qr, negm); }
;     const float alpha = softmax_rel(p0, p1, j == 0, m_reg, l_reg, pa0, pa1, pa2, pa3);
.LBB0_348:
	s_add_i32 s12, s10, 2
	s_cmp_lt_u32 s12, s74
	s_cselect_b64 s[56:57], -1, 0
	s_cmp_ge_u32 s12, s74
	s_cselect_b64 s[90:91], -1, 0
	s_mov_b32 s11, s24
	s_and_b64 vcc, exec, s[90:91]
	s_setprio 2
	v_lshl_add_u32 v212, s11, 14, v199
	v_add_u32_e32 v144, v212, v213
	ds_read_b128 v[194:197], v144 offset:0
	ds_read_b128 v[226:229], v144 offset:0x2000
	v_xor_b32_e32 v144, 32, v213
	v_add_u32_e32 v144, v212, v144
	ds_read_b128 v[230:233], v144 offset:0
	ds_read_b128 v[234:237], v144 offset:0x2000
	v_xor_b32_e32 v144, 64, v213
	v_add_u32_e32 v144, v212, v144
	ds_read_b128 v[238:241], v144 offset:0
	ds_read_b128 v[242:245], v144 offset:0x2000
	v_xor_b32_e32 v144, 0x60, v213
	v_add_u32_e32 v144, v212, v144
	ds_read_b128 v[246:249], v144 offset:0
	ds_read_b128 v[214:217], v144 offset:0x2000
	v_xor_b32_e32 v128, 0x80000000, v224
	v_mov_b32_e32 v129, v128
	v_mov_b32_e32 v130, v128
	v_mov_b32_e32 v131, v128
	v_mov_b32_e32 v132, v128
	v_mov_b32_e32 v133, v128
	v_mov_b32_e32 v134, v128
	v_mov_b32_e32 v135, v128
	v_mov_b32_e32 v136, v128
	v_mov_b32_e32 v137, v128
	v_mov_b32_e32 v138, v128
	v_mov_b32_e32 v139, v128
	v_mov_b32_e32 v140, v128
	v_mov_b32_e32 v141, v128
	v_mov_b32_e32 v142, v128
	v_mov_b32_e32 v143, v128
	s_waitcnt lgkmcnt(6)
	s_nop 1
	v_mfma_f32_32x32x16_bf16 v[144:159], v[194:197], v[188:191], v[128:143]
	v_mfma_f32_32x32x16_bf16 v[128:143], v[226:229], v[188:191], v[128:143]
	v_xor_b32_e32 v194, 0x80, v213
	v_add_u32_e32 v220, v212, v194
	ds_read_b128 v[194:197], v220 offset:0
	ds_read_b128 v[226:229], v220 offset:0x2000
	s_cbranch_vccnz .Lq0_nodma
	s_add_u32 s24, s38, 0xfffff000
	s_addc_u32 s25, s39, -1
	s_lshl_b32 s12, s9, 14
	s_add_i32 s12, s12, s0
	s_mov_b32 s13, m0
	s_mov_b32 m0, s12
	s_nop 0
	global_load_lds_dwordx4 v192, s[24:25]
	s_addk_i32 s12, 0x400
	s_mov_b32 m0, s12
	s_nop 0
	global_load_lds_dwordx4 v202, s[24:25]
	s_mov_b32 m0, s13
.Lq0_nodma:
	s_waitcnt lgkmcnt(6)
	v_mfma_f32_32x32x16_bf16 v[144:159], v[230:233], v[184:187], v[144:159]
	v_mfma_f32_32x32x16_bf16 v[128:143], v[234:237], v[184:187], v[128:143]
	v_xor_b32_e32 v220, 0xa0, v213
	v_add_u32_e32 v220, v212, v220
	ds_read_b128 v[230:233], v220 offset:0
	ds_read_b128 v[234:237], v220 offset:0x2000
	s_waitcnt lgkmcnt(6)
	v_mfma_f32_32x32x16_bf16 v[144:159], v[238:241], v[180:183], v[144:159]
	v_mfma_f32_32x32x16_bf16 v[128:143], v[242:245], v[180:183], v[128:143]
	v_xor_b32_e32 v220, 0xc0, v213
	v_add_u32_e32 v220, v212, v220
	ds_read_b128 v[238:241], v220 offset:0
	ds_read_b128 v[242:245], v220 offset:0x2000
	s_waitcnt lgkmcnt(6)
	v_mfma_f32_32x32x16_bf16 v[144:159], v[246:249], v[176:179], v[144:159]
	v_mfma_f32_32x32x16_bf16 v[128:143], v[214:217], v[176:179], v[128:143]
	v_xor_b32_e32 v214, 0xe0, v213
	v_add_u32_e32 v212, v212, v214
	ds_read_b128 v[214:217], v212 offset:0
	ds_read_b128 v[246:249], v212 offset:0x2000
	s_waitcnt lgkmcnt(6)
	v_mfma_f32_32x32x16_bf16 v[144:159], v[194:197], v[172:175], v[144:159]
	v_mfma_f32_32x32x16_bf16 v[128:143], v[226:229], v[172:175], v[128:143]
	s_waitcnt lgkmcnt(4)
	v_mfma_f32_32x32x16_bf16 v[144:159], v[230:233], v[168:171], v[144:159]
	v_mfma_f32_32x32x16_bf16 v[128:143], v[234:237], v[168:171], v[128:143]
	s_waitcnt lgkmcnt(2)
	v_mfma_f32_32x32x16_bf16 v[144:159], v[238:241], v[164:167], v[144:159]
	v_mfma_f32_32x32x16_bf16 v[128:143], v[242:245], v[164:167], v[128:143]
	s_waitcnt lgkmcnt(0)
	v_mfma_f32_32x32x16_bf16 v[144:159], v[214:217], v[160:163], v[144:159]
	s_cmp_eq_u32 s10, 0
	s_cselect_b64 s[62:63], -1, 0
	s_cmp_lg_u32 s10, 0
	v_mfma_f32_32x32x16_bf16 v[128:143], v[246:249], v[160:163], v[128:143]
	s_nop 7
	v_max_f32_e32 v194, v145, v145
	v_max_f32_e32 v195, v144, v144
	v_max_f32_e32 v194, v195, v194
	v_max3_f32 v194, v194, v146, v147
	v_max3_f32 v194, v194, v148, v149
	v_max3_f32 v194, v194, v150, v151
	v_max3_f32 v194, v194, v152, v153
	v_max3_f32 v194, v194, v154, v155
	v_max3_f32 v194, v194, v156, v157
	v_max3_f32 v194, v194, v158, v159
	v_max3_f32 v194, v194, v128, v129
	v_max3_f32 v194, v194, v130, v131
	v_max3_f32 v194, v194, v132, v133
	v_max3_f32 v194, v194, v134, v135
	v_max3_f32 v194, v194, v136, v137
	v_max3_f32 v194, v194, v138, v139
	v_max3_f32 v194, v194, v140, v141
	v_max3_f32 v194, v194, v142, v143
	v_mov_b32_e32 v195, v194
	s_nop 1
	v_permlane32_swap_b32_e32 v194, v195
	v_max_f32_e32 v195, v195, v195
	v_max_f32_e32 v194, v194, v194
	v_max_f32_e32 v226, v194, v195
	s_cbranch_scc0 .LBB0_371
	v_cmp_lt_f32_e32 vcc, s30, v226
	s_mov_b64 s[24:25], 0
	s_mov_b64 s[96:97], 0
	s_cbranch_vccnz .LBB0_372
	s_and_b64 vcc, exec, s[24:25]
	s_cbranch_vccnz .LBB0_373

; #define SBAR() __builtin_amdgcn_sched_barrier(0)
; #define VF_WAIT(N) do { asm volatile("s_waitcnt lgkmcnt(" #N ")" ::: "memory"); SBAR(); } while (0)
; #define DMA_V(t, sl) do { const char* b_ = Vb + (size_t)(t) * TSTRIDE; const unsigned d_ = RFL(vdst + (sl) * 32768); glds16(b_ + voff[0], d_); glds16(b_ + voff[1], d_ + 1024); glds16(b_ + voff[2], d_ + 2048); glds16(b_ + voff[3], d_ + 3072); } while (0)
; __device__ __forceinline__ void pv8(f32x16* o, int vb, bf16x8 pa0, bf16x8 pa1, bf16x8 pa2, bf16x8 pa3) {
;   VFrag fa, fb; const int vb2 = vb + 16384;
;   vf_read<0>(fa, vb);
;   vf_read<1>(fb, vb);  VF_WAIT(8); vf_mma(o[0], fa, pa0, pa1, pa2, pa3); SBAR();
;   vf_read<2>(fa, vb);  VF_WAIT(8); vf_mma(o[1], fb, pa0, pa1, pa2, pa3); SBAR();
;   vf_read<3>(fb, vb);  VF_WAIT(8); vf_mma(o[2], fa, pa0, pa1, pa2, pa3); SBAR();
;   vf_read<0>(fa, vb2); VF_WAIT(8); vf_mma(o[3], fb, pa0, pa1, pa2, pa3); SBAR();
;   vf_read<1>(fb, vb2); VF_WAIT(8); vf_mma(o[4], fa, pa0, pa1, pa2, pa3); SBAR();
;   vf_read<2>(fa, vb2); VF_WAIT(8); vf_mma(o[5], fb, pa0, pa1, pa2, pa3); SBAR();
;   vf_read<3>(fb, vb2); VF_WAIT(8); vf_mma(o[6], fa, pa0, pa1, pa2, pa3); SBAR();
;   VF_WAIT(0); vf_mma(o[7], fb, pa0, pa1, pa2, pa3);
; }
; template <int mode> ...
;     ...
;     if (more) DMA_V(j + 2, s2);
;     pv8(o, vb0 + s0 * 32768, pa0, pa1, pa2, pa3);
.LBB0_363:
	v_lshl_add_u32 v220, s11, 15, v223
	ds_read_b64_tr_b16 v[144:145], v220 offset:0
	ds_read_b64_tr_b16 v[146:147], v220 offset:0x800
	ds_read_b64_tr_b16 v[148:149], v220 offset:0x1000
	ds_read_b64_tr_b16 v[150:151], v220 offset:0x1800
	ds_read_b64_tr_b16 v[152:153], v220 offset:0x2000
	ds_read_b64_tr_b16 v[154:155], v220 offset:0x2800
	ds_read_b64_tr_b16 v[156:157], v220 offset:0x3000
	ds_read_b64_tr_b16 v[158:159], v220 offset:0x3800
	ds_read_b64_tr_b16 v[194:195], v220 offset:0x200
	ds_read_b64_tr_b16 v[196:197], v220 offset:0xa00
	ds_read_b64_tr_b16 v[214:215], v220 offset:0x1200
	ds_read_b64_tr_b16 v[216:217], v220 offset:0x1a00
	ds_read_b64_tr_b16 v[228:229], v220 offset:0x2200
	ds_read_b64_tr_b16 v[230:231], v220 offset:0x2a00
	ds_read_b64_tr_b16 v[232:233], v220 offset:0x3200
	ds_read_b64_tr_b16 v[234:235], v220 offset:0x3a00
	s_waitcnt lgkmcnt(8)
	v_add_u32_e32 v221, 0x4000, v220
	v_mfma_f32_32x32x16_bf16 v[112:127], v[128:131], v[144:147], v[112:127]
	v_mfma_f32_32x32x16_bf16 v[112:127], v[132:135], v[148:151], v[112:127]
	v_mfma_f32_32x32x16_bf16 v[112:127], v[136:139], v[152:155], v[112:127]
	v_mfma_f32_32x32x16_bf16 v[112:127], v[140:143], v[156:159], v[112:127]
	ds_read_b64_tr_b16 v[144:145], v220 offset:0x400
	ds_read_b64_tr_b16 v[146:147], v220 offset:0xc00
	ds_read_b64_tr_b16 v[148:149], v220 offset:0x1400
	ds_read_b64_tr_b16 v[150:151], v220 offset:0x1c00
	ds_read_b64_tr_b16 v[152:153], v220 offset:0x2400
	ds_read_b64_tr_b16 v[154:155], v220 offset:0x2c00
	ds_read_b64_tr_b16 v[156:157], v220 offset:0x3400
	ds_read_b64_tr_b16 v[158:159], v220 offset:0x3c00
	s_cbranch_vccnz .Lp0_nodma
	s_lshl_b32 s12, s9, 15
	s_add_i32 s12, s12, s7
	s_mov_b32 s13, m0
	s_mov_b32 m0, s12
	s_nop 0
	global_load_lds_dwordx4 v204, s[38:39]
	s_add_i32 s24, s12, 0x400
	s_mov_b32 m0, s24
	s_nop 0
	global_load_lds_dwordx4 v206, s[38:39]
	s_add_i32 s24, s12, 0x800
	s_mov_b32 m0, s24
	s_nop 0
	global_load_lds_dwordx4 v208, s[38:39]
	s_add_i32 s24, s12, 0xc00
	s_mov_b32 m0, s24
	s_nop 0
	global_load_lds_dwordx4 v210, s[38:39]
	s_mov_b32 m0, s13
.Lp0_nodma:
	s_waitcnt lgkmcnt(8)
	v_mfma_f32_32x32x16_bf16 v[96:111], v[128:131], v[194:197], v[96:111]
	v_mfma_f32_32x32x16_bf16 v[96:111], v[132:135], v[214:217], v[96:111]
	v_mfma_f32_32x32x16_bf16 v[96:111], v[136:139], v[228:231], v[96:111]
	v_mfma_f32_32x32x16_bf16 v[96:111], v[140:143], v[232:235], v[96:111]
	ds_read_b64_tr_b16 v[194:195], v220 offset:0x600
	ds_read_b64_tr_b16 v[196:197], v220 offset:0xe00
	ds_read_b64_tr_b16 v[214:215], v220 offset:0x1600
	ds_read_b64_tr_b16 v[216:217], v220 offset:0x1e00
	ds_read_b64_tr_b16 v[228:229], v220 offset:0x2600
	ds_read_b64_tr_b16 v[230:231], v220 offset:0x2e00
	ds_read_b64_tr_b16 v[232:233], v220 offset:0x3600
	ds_read_b64_tr_b16 v[234:235], v220 offset:0x3e00
	s_waitcnt lgkmcnt(8)
	v_mfma_f32_32x32x16_bf16 v[80:95], v[128:131], v[144:147], v[80:95]
	v_mfma_f32_32x32x16_bf16 v[80:95], v[132:135], v[148:151], v[80:95]
	v_mfma_f32_32x32x16_bf16 v[80:95], v[136:139], v[152:155], v[80:95]
	v_mfma_f32_32x32x16_bf16 v[80:95], v[140:143], v[156:159], v[80:95]
	ds_read_b64_tr_b16 v[144:145], v221 offset:0
	ds_read_b64_tr_b16 v[146:147], v221 offset:0x800
	ds_read_b64_tr_b16 v[148:149], v221 offset:0x1000
	ds_read_b64_tr_b16 v[150:151], v221 offset:0x1800
	ds_read_b64_tr_b16 v[152:153], v221 offset:0x2000
	ds_read_b64_tr_b16 v[154:155], v221 offset:0x2800
	ds_read_b64_tr_b16 v[156:157], v221 offset:0x3000
	ds_read_b64_tr_b16 v[158:159], v221 offset:0x3800
	s_waitcnt lgkmcnt(8)
	v_mfma_f32_32x32x16_bf16 v[64:79], v[128:131], v[194:197], v[64:79]
	v_mfma_f32_32x32x16_bf16 v[64:79], v[132:135], v[214:217], v[64:79]
	v_mfma_f32_32x32x16_bf16 v[64:79], v[136:139], v[228:231], v[64:79]
	v_mfma_f32_32x32x16_bf16 v[64:79], v[140:143], v[232:235], v[64:79]
	ds_read_b64_tr_b16 v[194:195], v221 offset:0x200
	ds_read_b64_tr_b16 v[196:197], v221 offset:0xa00
	ds_read_b64_tr_b16 v[214:215], v221 offset:0x1200
	ds_read_b64_tr_b16 v[216:217], v221 offset:0x1a00
	ds_read_b64_tr_b16 v[228:229], v221 offset:0x2200
	ds_read_b64_tr_b16 v[230:231], v221 offset:0x2a00
	ds_read_b64_tr_b16 v[232:233], v221 offset:0x3200
	ds_read_b64_tr_b16 v[234:235], v221 offset:0x3a00
	s_waitcnt lgkmcnt(8)
	v_mfma_f32_32x32x16_bf16 v[48:63], v[128:131], v[144:147], v[48:63]
	v_mfma_f32_32x32x16_bf16 v[48:63], v[132:135], v[148:151], v[48:63]
	v_mfma_f32_32x32x16_bf16 v[48:63], v[136:139], v[152:155], v[48:63]
	v_mfma_f32_32x32x16_bf16 v[48:63], v[140:143], v[156:159], v[48:63]
	ds_read_b64_tr_b16 v[144:145], v221 offset:0x400
	ds_read_b64_tr_b16 v[146:147], v221 offset:0xc00
	ds_read_b64_tr_b16 v[148:149], v221 offset:0x1400
	ds_read_b64_tr_b16 v[150:151], v221 offset:0x1c00
	ds_read_b64_tr_b16 v[152:153], v221 offset:0x2400
	ds_read_b64_tr_b16 v[154:155], v221 offset:0x2c00
	ds_read_b64_tr_b16 v[156:157], v221 offset:0x3400
	ds_read_b64_tr_b16 v[158:159], v221 offset:0x3c00
	s_waitcnt lgkmcnt(8)
	v_mfma_f32_32x32x16_bf16 v[32:47], v[128:131], v[194:197], v[32:47]
	v_mfma_f32_32x32x16_bf16 v[32:47], v[132:135], v[214:217], v[32:47]
	v_mfma_f32_32x32x16_bf16 v[32:47], v[136:139], v[228:231], v[32:47]
	v_mfma_f32_32x32x16_bf16 v[32:47], v[140:143], v[232:235], v[32:47]
	ds_read_b64_tr_b16 v[194:195], v221 offset:0x600
	ds_read_b64_tr_b16 v[196:197], v221 offset:0xe00
	ds_read_b64_tr_b16 v[214:215], v221 offset:0x1600
	ds_read_b64_tr_b16 v[216:217], v221 offset:0x1e00
	ds_read_b64_tr_b16 v[228:229], v221 offset:0x2600
	ds_read_b64_tr_b16 v[230:231], v221 offset:0x2e00
	ds_read_b64_tr_b16 v[232:233], v221 offset:0x3600
	ds_read_b64_tr_b16 v[234:235], v221 offset:0x3e00
	s_waitcnt lgkmcnt(8)
	v_mfma_f32_32x32x16_bf16 v[16:31], v[128:131], v[144:147], v[16:31]
	v_mfma_f32_32x32x16_bf16 v[16:31], v[132:135], v[148:151], v[16:31]
	v_mfma_f32_32x32x16_bf16 v[16:31], v[136:139], v[152:155], v[16:31]
	v_mfma_f32_32x32x16_bf16 v[16:31], v[140:143], v[156:159], v[16:31]
	s_waitcnt lgkmcnt(0)
	v_mfma_f32_32x32x16_bf16 v[0:15], v[128:131], v[194:197], v[0:15]
	s_mov_b64 s[24:25], -1
	s_and_b64 vcc, exec, s[90:91]
	v_mfma_f32_32x32x16_bf16 v[0:15], v[132:135], v[214:217], v[0:15]
	v_mfma_f32_32x32x16_bf16 v[0:15], v[136:139], v[228:231], v[0:15]
	v_mfma_f32_32x32x16_bf16 v[0:15], v[140:143], v[232:235], v[0:15]
	s_cbranch_vccz .LBB0_365
	s_waitcnt vmcnt(0) lgkmcnt(0)
	s_barrier
	s_mov_b64 s[24:25], 0

; #define SBAR() __builtin_amdgcn_sched_barrier(0)
; #define KRD(A, B, d0) do { const int ad_ = (kc ^ ((d0) << 5)) + kbt; A = lds_rd128<0>(ad_); B = lds_rd128<8192>(ad_); } while (0)
; #define KW(N) do { asm volatile("s_waitcnt lgkmcnt(" #N ")" ::: "memory"); SBAR(); } while (0)
; __device__ __forceinline__ void qkt_pipe(f32x16& p0, f32x16& p1, int kbt, int kc, const bf16x8* qr, const f32x16& z) {
;   bf16x8 a0, b0, a1, b1, a2, b2, a3, b3;
;     ...
;   KRD(a0, b0, 0); KRD(a1, b1, 1); KRD(a2, b2, 2); KRD(a3, b3, 3);
;   KW(6); p0 = __builtin_amdgcn_mfma_f32_32x32x16_bf16(a0, qr[0], z, 0, 0, 0);  p1 = __builtin_amdgcn_mfma_f32_32x32x16_bf16(b0, qr[0], z, 0, 0, 0);  SBAR(); KRD(a0, b0, 4);
;   KW(6); p0 = __builtin_amdgcn_mfma_f32_32x32x16_bf16(a1, qr[1], p0, 0, 0, 0); p1 = __builtin_amdgcn_mfma_f32_32x32x16_bf16(b1, qr[1], p1, 0, 0, 0); SBAR(); KRD(a1, b1, 5);
;   KW(6); p0 = __builtin_amdgcn_mfma_f32_32x32x16_bf16(a2, qr[2], p0, 0, 0, 0); p1 = __builtin_amdgcn_mfma_f32_32x32x16_bf16(b2, qr[2], p1, 0, 0, 0); SBAR(); KRD(a2, b2, 6);
;   KW(6); p0 = __builtin_amdgcn_mfma_f32_32x32x16_bf16(a3, qr[3], p0, 0, 0, 0); p1 = __builtin_amdgcn_mfma_f32_32x32x16_bf16(b3, qr[3], p1, 0, 0, 0); SBAR(); KRD(a3, b3, 7);
;   KW(6); p0 = __builtin_amdgcn_mfma_f32_32x32x16_bf16(a0, qr[4], p0, 0, 0, 0); p1 = __builtin_amdgcn_mfma_f32_32x32x16_bf16(b0, qr[4], p1, 0, 0, 0); SBAR();
;   KW(4); p0 = __builtin_amdgcn_mfma_f32_32x32x16_bf16(a1, qr[5], p0, 0, 0, 0); p1 = __builtin_amdgcn_mfma_f32_32x32x16_bf16(b1, qr[5], p1, 0, 0, 0); SBAR();
;   KW(2); p0 = __builtin_amdgcn_mfma_f32_32x32x16_bf16(a2, qr[6], p0, 0, 0, 0); p1 = __builtin_amdgcn_mfma_f32_32x32x16_bf16(b2, qr[6], p1, 0, 0, 0); SBAR();
;   KW(0); p0 = __builtin_amdgcn_mfma_f32_32x32x16_bf16(a3, qr[7], p0, 0, 0, 0); p1 = __builtin_amdgcn_mfma_f32_32x32x16_bf16(b3, qr[7], p1, 0, 0, 0);
; template <int mode> ...
;     ...
;   for (int j = 0; j < NT; ++j) {
;     const bool more = j + 2 < NT;
;     if (more) DMA_K(j + 2, s2);
;     f32x16 p0, p1; bf16x8 pa0, pa1, pa2, pa3;
;     __builtin_amdgcn_s_setprio(2);
;     { f32x16 negm;
; #pragma unroll
;       for (int r = 0; r < 16; ++r) negm[r] = -m_reg;
;       qkt_pipe(p0, p1, kb0 + s0 * 16384, kc, qr, negm); }
;     const float alpha = softmax_rel(p0, p1, j == 0, m_reg, l_reg, pa0, pa1, pa2, pa3);
.LBB0_381:
	s_mov_b32 s10, s11
	s_add_i32 s11, s9, 2
	s_cmp_lt_u32 s11, s74
	s_cselect_b64 s[52:53], -1, 0
	s_cmp_ge_u32 s11, s74
	s_cselect_b64 s[50:51], -1, 0
	s_and_b64 vcc, exec, s[50:51]
	s_setprio 2
	v_lshl_add_u32 v212, s10, 14, v201
	v_add_u32_e32 v144, v212, v225
	ds_read_b128 v[194:197], v144 offset:0
	ds_read_b128 v[214:217], v144 offset:0x2000
	v_xor_b32_e32 v144, 32, v225
	v_add_u32_e32 v144, v212, v144
	ds_read_b128 v[230:233], v144 offset:0
	ds_read_b128 v[234:237], v144 offset:0x2000
	v_xor_b32_e32 v144, 64, v225
	v_add_u32_e32 v144, v212, v144
	ds_read_b128 v[238:241], v144 offset:0
	ds_read_b128 v[242:245], v144 offset:0x2000
	v_xor_b32_e32 v144, 0x60, v225
	v_add_u32_e32 v144, v212, v144
	ds_read_b128 v[246:249], v144 offset:0
	ds_read_b128 v[220:223], v144 offset:0x2000
	v_xor_b32_e32 v128, 0x80000000, v227
	v_mov_b32_e32 v129, v128
	v_mov_b32_e32 v130, v128
	v_mov_b32_e32 v131, v128
	v_mov_b32_e32 v132, v128
	v_mov_b32_e32 v133, v128
	v_mov_b32_e32 v134, v128
	v_mov_b32_e32 v135, v128
	v_mov_b32_e32 v136, v128
	v_mov_b32_e32 v137, v128
	v_mov_b32_e32 v138, v128
	v_mov_b32_e32 v139, v128
	v_mov_b32_e32 v140, v128
	v_mov_b32_e32 v141, v128
	v_mov_b32_e32 v142, v128
	v_mov_b32_e32 v143, v128
	s_waitcnt lgkmcnt(6)
	s_nop 1
	v_mfma_f32_32x32x16_bf16 v[144:159], v[194:197], v[188:191], v[128:143]
	v_mfma_f32_32x32x16_bf16 v[128:143], v[214:217], v[188:191], v[128:143]
	v_xor_b32_e32 v194, 0x80, v225
	v_add_u32_e32 v229, v212, v194
	ds_read_b128 v[194:197], v229 offset:0
	ds_read_b128 v[214:217], v229 offset:0x2000
	s_cbranch_vccnz .Lq1_nodma
	s_add_u32 s24, s60, 0xfffff100
	s_addc_u32 s25, s61, -1
	s_lshl_b32 s11, s7, 14
	s_add_i32 s11, s11, s0
	s_mov_b32 s12, m0
	s_mov_b32 m0, s11
	s_nop 0
	global_load_lds_dwordx4 v192, s[24:25]
	s_addk_i32 s11, 0x400
	s_mov_b32 m0, s11
	s_nop 0
	global_load_lds_dwordx4 v202, s[24:25]
	s_mov_b32 m0, s12
.Lq1_nodma:
	s_waitcnt lgkmcnt(6)
	v_mfma_f32_32x32x16_bf16 v[144:159], v[230:233], v[184:187], v[144:159]
	v_mfma_f32_32x32x16_bf16 v[128:143], v[234:237], v[184:187], v[128:143]
	v_xor_b32_e32 v229, 0xa0, v225
	v_add_u32_e32 v229, v212, v229
	ds_read_b128 v[230:233], v229 offset:0
	ds_read_b128 v[234:237], v229 offset:0x2000
	s_waitcnt lgkmcnt(6)
	v_mfma_f32_32x32x16_bf16 v[144:159], v[238:241], v[180:183], v[144:159]
	v_mfma_f32_32x32x16_bf16 v[128:143], v[242:245], v[180:183], v[128:143]
	v_xor_b32_e32 v229, 0xc0, v225
	v_add_u32_e32 v229, v212, v229
	ds_read_b128 v[238:241], v229 offset:0
	ds_read_b128 v[242:245], v229 offset:0x2000
	s_waitcnt lgkmcnt(6)
	v_mfma_f32_32x32x16_bf16 v[144:159], v[246:249], v[176:179], v[144:159]
	v_mfma_f32_32x32x16_bf16 v[128:143], v[220:223], v[176:179], v[128:143]
	v_xor_b32_e32 v220, 0xe0, v225
	v_add_u32_e32 v212, v212, v220
	ds_read_b128 v[220:223], v212 offset:0
	ds_read_b128 v[246:249], v212 offset:0x2000
	s_waitcnt lgkmcnt(6)
	v_mfma_f32_32x32x16_bf16 v[144:159], v[194:197], v[172:175], v[144:159]
	v_mfma_f32_32x32x16_bf16 v[128:143], v[214:217], v[172:175], v[128:143]
	s_waitcnt lgkmcnt(4)
	v_mfma_f32_32x32x16_bf16 v[144:159], v[230:233], v[168:171], v[144:159]
	v_mfma_f32_32x32x16_bf16 v[128:143], v[234:237], v[168:171], v[128:143]
	s_waitcnt lgkmcnt(2)
	v_mfma_f32_32x32x16_bf16 v[144:159], v[238:241], v[164:167], v[144:159]
	v_mfma_f32_32x32x16_bf16 v[128:143], v[242:245], v[164:167], v[128:143]
	s_waitcnt lgkmcnt(0)
	v_mfma_f32_32x32x16_bf16 v[144:159], v[220:223], v[160:163], v[144:159]
	s_cmp_eq_u32 s9, 0
	s_cselect_b64 s[56:57], -1, 0
	s_cmp_lg_u32 s9, 0
	v_mfma_f32_32x32x16_bf16 v[128:143], v[246:249], v[160:163], v[128:143]
	s_nop 7
	v_max_f32_e32 v194, v145, v145
	v_max_f32_e32 v195, v144, v144
	v_max_f32_e32 v194, v195, v194
	v_max3_f32 v194, v194, v146, v147
	v_max3_f32 v194, v194, v148, v149
	v_max3_f32 v194, v194, v150, v151
	v_max3_f32 v194, v194, v152, v153
	v_max3_f32 v194, v194, v154, v155
	v_max3_f32 v194, v194, v156, v157
	v_max3_f32 v194, v194, v158, v159
	v_max3_f32 v194, v194, v128, v129
	v_max3_f32 v194, v194, v130, v131
	v_max3_f32 v194, v194, v132, v133
	v_max3_f32 v194, v194, v134, v135
	v_max3_f32 v194, v194, v136, v137
	v_max3_f32 v194, v194, v138, v139
	v_max3_f32 v194, v194, v140, v141
	v_max3_f32 v194, v194, v142, v143
	v_mov_b32_e32 v195, v194
	s_nop 1
	v_permlane32_swap_b32_e32 v194, v195
	v_max_f32_e32 v195, v195, v195
	v_max_f32_e32 v194, v194, v194
	v_max_f32_e32 v229, v194, v195
	s_cbranch_scc0 .LBB0_404
	v_cmp_lt_f32_e32 vcc, s30, v229
	s_mov_b64 s[24:25], 0
	s_mov_b64 s[62:63], 0
	s_cbranch_vccnz .LBB0_405
	s_and_b64 vcc, exec, s[24:25]
	s_cbranch_vccnz .LBB0_406

; #define SBAR() __builtin_amdgcn_sched_barrier(0)
; #define VF_WAIT(N) do { asm volatile("s_waitcnt lgkmcnt(" #N ")" ::: "memory"); SBAR(); } while (0)
; #define DMA_V(t, sl) do { const char* b_ = Vb + (size_t)(t) * TSTRIDE; const unsigned d_ = RFL(vdst + (sl) * 32768); glds16(b_ + voff[0], d_); glds16(b_ + voff[1], d_ + 1024); glds16(b_ + voff[2], d_ + 2048); glds16(b_ + voff[3], d_ + 3072); } while (0)
; __device__ __forceinline__ void pv8(f32x16* o, int vb, bf16x8 pa0, bf16x8 pa1, bf16x8 pa2, bf16x8 pa3) {
;   VFrag fa, fb; const int vb2 = vb + 16384;
;   vf_read<0>(fa, vb);
;   vf_read<1>(fb, vb);  VF_WAIT(8); vf_mma(o[0], fa, pa0, pa1, pa2, pa3); SBAR();
;   vf_read<2>(fa, vb);  VF_WAIT(8); vf_mma(o[1], fb, pa0, pa1, pa2, pa3); SBAR();
;   vf_read<3>(fb, vb);  VF_WAIT(8); vf_mma(o[2], fa, pa0, pa1, pa2, pa3); SBAR();
;   vf_read<0>(fa, vb2); VF_WAIT(8); vf_mma(o[3], fb, pa0, pa1, pa2, pa3); SBAR();
;   vf_read<1>(fb, vb2); VF_WAIT(8); vf_mma(o[4], fa, pa0, pa1, pa2, pa3); SBAR();
;   vf_read<2>(fa, vb2); VF_WAIT(8); vf_mma(o[5], fb, pa0, pa1, pa2, pa3); SBAR();
;   vf_read<3>(fb, vb2); VF_WAIT(8); vf_mma(o[6], fa, pa0, pa1, pa2, pa3); SBAR();
;   VF_WAIT(0); vf_mma(o[7], fb, pa0, pa1, pa2, pa3);
; }
; template <int mode> ...
;     ...
;     if (more) DMA_V(j + 2, s2);
;     pv8(o, vb0 + s0 * 32768, pa0, pa1, pa2, pa3);
.LBB0_396:
	v_lshl_add_u32 v231, s10, 15, v226
	ds_read_b64_tr_b16 v[144:145], v231 offset:0
	ds_read_b64_tr_b16 v[146:147], v231 offset:0x800
	ds_read_b64_tr_b16 v[148:149], v231 offset:0x1000
	ds_read_b64_tr_b16 v[150:151], v231 offset:0x1800
	ds_read_b64_tr_b16 v[152:153], v231 offset:0x2000
	ds_read_b64_tr_b16 v[154:155], v231 offset:0x2800
	ds_read_b64_tr_b16 v[156:157], v231 offset:0x3000
	ds_read_b64_tr_b16 v[158:159], v231 offset:0x3800
	ds_read_b64_tr_b16 v[194:195], v231 offset:0x200
	ds_read_b64_tr_b16 v[196:197], v231 offset:0xa00
	ds_read_b64_tr_b16 v[214:215], v231 offset:0x1200
	ds_read_b64_tr_b16 v[216:217], v231 offset:0x1a00
	ds_read_b64_tr_b16 v[220:221], v231 offset:0x2200
	ds_read_b64_tr_b16 v[222:223], v231 offset:0x2a00
	ds_read_b64_tr_b16 v[232:233], v231 offset:0x3200
	ds_read_b64_tr_b16 v[234:235], v231 offset:0x3a00
	s_waitcnt lgkmcnt(8)
	v_add_u32_e32 v236, 0x4000, v231
	v_mfma_f32_32x32x16_bf16 v[16:31], v[128:131], v[144:147], v[16:31]
	v_mfma_f32_32x32x16_bf16 v[16:31], v[132:135], v[148:151], v[16:31]
	v_mfma_f32_32x32x16_bf16 v[16:31], v[136:139], v[152:155], v[16:31]
	v_mfma_f32_32x32x16_bf16 v[16:31], v[140:143], v[156:159], v[16:31]
	ds_read_b64_tr_b16 v[144:145], v231 offset:0x400
	ds_read_b64_tr_b16 v[146:147], v231 offset:0xc00
	ds_read_b64_tr_b16 v[148:149], v231 offset:0x1400
	ds_read_b64_tr_b16 v[150:151], v231 offset:0x1c00
	ds_read_b64_tr_b16 v[152:153], v231 offset:0x2400
	ds_read_b64_tr_b16 v[154:155], v231 offset:0x2c00
	ds_read_b64_tr_b16 v[156:157], v231 offset:0x3400
	ds_read_b64_tr_b16 v[158:159], v231 offset:0x3c00
	s_cbranch_vccnz .Lp1_nodma
	s_lshl_b32 s11, s7, 15
	s_add_i32 s11, s11, s5
	s_mov_b32 s12, m0
	s_mov_b32 m0, s11
	s_nop 0
	global_load_lds_dwordx4 v204, s[60:61]
	s_add_i32 s13, s11, 0x400
	s_mov_b32 m0, s13
	s_nop 0
	global_load_lds_dwordx4 v206, s[60:61]
	s_add_i32 s13, s11, 0x800
	s_mov_b32 m0, s13
	s_nop 0
	global_load_lds_dwordx4 v208, s[60:61]
	s_add_i32 s13, s11, 0xc00
	s_mov_b32 m0, s13
	s_nop 0
	global_load_lds_dwordx4 v210, s[60:61]
	s_mov_b32 m0, s12
.Lp1_nodma:
	s_waitcnt lgkmcnt(8)
	v_mfma_f32_32x32x16_bf16 v[32:47], v[128:131], v[194:197], v[32:47]
	v_mfma_f32_32x32x16_bf16 v[32:47], v[132:135], v[214:217], v[32:47]
	v_mfma_f32_32x32x16_bf16 v[32:47], v[136:139], v[220:223], v[32:47]
	v_mfma_f32_32x32x16_bf16 v[32:47], v[140:143], v[232:235], v[32:47]
	ds_read_b64_tr_b16 v[194:195], v231 offset:0x600
	ds_read_b64_tr_b16 v[196:197], v231 offset:0xe00
	ds_read_b64_tr_b16 v[214:215], v231 offset:0x1600
	ds_read_b64_tr_b16 v[216:217], v231 offset:0x1e00
	ds_read_b64_tr_b16 v[220:221], v231 offset:0x2600
	ds_read_b64_tr_b16 v[222:223], v231 offset:0x2e00
	ds_read_b64_tr_b16 v[232:233], v231 offset:0x3600
	ds_read_b64_tr_b16 v[234:235], v231 offset:0x3e00
	s_waitcnt lgkmcnt(8)
	v_mfma_f32_32x32x16_bf16 v[96:111], v[128:131], v[144:147], v[96:111]
	v_mfma_f32_32x32x16_bf16 v[96:111], v[132:135], v[148:151], v[96:111]
	v_mfma_f32_32x32x16_bf16 v[96:111], v[136:139], v[152:155], v[96:111]
	v_mfma_f32_32x32x16_bf16 v[96:111], v[140:143], v[156:159], v[96:111]
	ds_read_b64_tr_b16 v[144:145], v236 offset:0
	ds_read_b64_tr_b16 v[146:147], v236 offset:0x800
	ds_read_b64_tr_b16 v[148:149], v236 offset:0x1000
	ds_read_b64_tr_b16 v[150:151], v236 offset:0x1800
	ds_read_b64_tr_b16 v[152:153], v236 offset:0x2000
	ds_read_b64_tr_b16 v[154:155], v236 offset:0x2800
	ds_read_b64_tr_b16 v[156:157], v236 offset:0x3000
	ds_read_b64_tr_b16 v[158:159], v236 offset:0x3800
	s_waitcnt lgkmcnt(8)
	v_mfma_f32_32x32x16_bf16 v[112:127], v[128:131], v[194:197], v[112:127]
	v_mfma_f32_32x32x16_bf16 v[112:127], v[132:135], v[214:217], v[112:127]
	v_mfma_f32_32x32x16_bf16 v[112:127], v[136:139], v[220:223], v[112:127]
	v_mfma_f32_32x32x16_bf16 v[112:127], v[140:143], v[232:235], v[112:127]
	ds_read_b64_tr_b16 v[194:195], v236 offset:0x200
	ds_read_b64_tr_b16 v[196:197], v236 offset:0xa00
	ds_read_b64_tr_b16 v[214:215], v236 offset:0x1200
	ds_read_b64_tr_b16 v[216:217], v236 offset:0x1a00
	ds_read_b64_tr_b16 v[220:221], v236 offset:0x2200
	ds_read_b64_tr_b16 v[222:223], v236 offset:0x2a00
	ds_read_b64_tr_b16 v[232:233], v236 offset:0x3200
	ds_read_b64_tr_b16 v[234:235], v236 offset:0x3a00
	s_waitcnt lgkmcnt(8)
	v_mfma_f32_32x32x16_bf16 v[64:79], v[128:131], v[144:147], v[64:79]
	v_mfma_f32_32x32x16_bf16 v[64:79], v[132:135], v[148:151], v[64:79]
	v_mfma_f32_32x32x16_bf16 v[64:79], v[136:139], v[152:155], v[64:79]
	v_mfma_f32_32x32x16_bf16 v[64:79], v[140:143], v[156:159], v[64:79]
	ds_read_b64_tr_b16 v[144:145], v236 offset:0x400
	ds_read_b64_tr_b16 v[146:147], v236 offset:0xc00
	ds_read_b64_tr_b16 v[148:149], v236 offset:0x1400
	ds_read_b64_tr_b16 v[150:151], v236 offset:0x1c00
	ds_read_b64_tr_b16 v[152:153], v236 offset:0x2400
	ds_read_b64_tr_b16 v[154:155], v236 offset:0x2c00
	ds_read_b64_tr_b16 v[156:157], v236 offset:0x3400
	ds_read_b64_tr_b16 v[158:159], v236 offset:0x3c00
	s_waitcnt lgkmcnt(8)
	v_mfma_f32_32x32x16_bf16 v[48:63], v[128:131], v[194:197], v[48:63]
	v_mfma_f32_32x32x16_bf16 v[48:63], v[132:135], v[214:217], v[48:63]
	v_mfma_f32_32x32x16_bf16 v[48:63], v[136:139], v[220:223], v[48:63]
	v_mfma_f32_32x32x16_bf16 v[48:63], v[140:143], v[232:235], v[48:63]
	ds_read_b64_tr_b16 v[194:195], v236 offset:0x600
	ds_read_b64_tr_b16 v[196:197], v236 offset:0xe00
	ds_read_b64_tr_b16 v[214:215], v236 offset:0x1600
	ds_read_b64_tr_b16 v[216:217], v236 offset:0x1e00
	ds_read_b64_tr_b16 v[220:221], v236 offset:0x2600
	ds_read_b64_tr_b16 v[222:223], v236 offset:0x2e00
	ds_read_b64_tr_b16 v[232:233], v236 offset:0x3600
	ds_read_b64_tr_b16 v[234:235], v236 offset:0x3e00
	s_waitcnt lgkmcnt(8)
	v_mfma_f32_32x32x16_bf16 v[0:15], v[128:131], v[144:147], v[0:15]
	v_mfma_f32_32x32x16_bf16 v[0:15], v[132:135], v[148:151], v[0:15]
	v_mfma_f32_32x32x16_bf16 v[0:15], v[136:139], v[152:155], v[0:15]
	v_mfma_f32_32x32x16_bf16 v[0:15], v[140:143], v[156:159], v[0:15]
	s_waitcnt lgkmcnt(0)
	v_mfma_f32_32x32x16_bf16 v[80:95], v[128:131], v[194:197], v[80:95]
	s_mov_b64 s[24:25], -1
	s_and_b64 vcc, exec, s[50:51]
	v_mfma_f32_32x32x16_bf16 v[80:95], v[132:135], v[214:217], v[80:95]
	v_mfma_f32_32x32x16_bf16 v[80:95], v[136:139], v[220:223], v[80:95]
	v_mfma_f32_32x32x16_bf16 v[80:95], v[140:143], v[232:235], v[80:95]
	s_cbranch_vccz .LBB0_398
	s_waitcnt vmcnt(0) lgkmcnt(0)
	s_barrier
	s_mov_b64 s[24:25], 0

; __device__ __forceinline__ float bflo(unsigned w) { return __uint_as_float(w << 16); }
; __device__ __forceinline__ float bfhi(unsigned w) { return __uint_as_float(w & 0xffff0000u); }
; __global__ void __launch_bounds__(NWAVES * 64, 2) mega_fwd(Args args) {
;     ...
;             const bf16* xr = XB + (size_t)row * DM; const bf16* mr = MP + (size_t)row * DM; float* yr = outg + (size_t)row * DM; f32x4 v[16]; float s = 0.f;
; #pragma unroll
;             for (int j = 0; j < 16; ++j) { const v2u xv = *(const v2u*)(xr + 4 * lane + 256 * j); const v2u m = *(const v2u*)(mr + 4 * lane + 256 * j);
;                 v[j] = (f32x4){bflo(xv[0]), bfhi(xv[0]), bflo(xv[1]), bfhi(xv[1])} * DEEP_ALPHA + (f32x4){bflo(m[0]), bfhi(m[0]), bflo(m[1]), bfhi(m[1])}; s += (v[j][0] + v[j][1]) + (v[j][2] + v[j][3]); }
.LBB0_662:
	s_nop 1
	v_add_co_u32_e32 v82, vcc, 0xdffff000, v52
	s_brev_b32 s0, 7
	s_nop 0
	v_addc_co_u32_e32 v83, vcc, -1, v53, vcc
	v_add_co_u32_e32 v70, vcc, 0xfffff000, v52
	global_load_dwordx2 v[138:139], v[82:83], off offset:-3584
	s_nop 0
	v_addc_co_u32_e32 v71, vcc, -1, v53, vcc
	global_load_dwordx2 v[140:141], v[70:71], off offset:-3584
	v_add_co_u32_e32 v114, vcc, s0, v52
	s_nop 1
	v_addc_co_u32_e32 v115, vcc, -1, v53, vcc
	s_nop 0
	global_load_dwordx2 v[142:143], v[82:83], off offset:-3072
	global_load_dwordx2 v[144:145], v[70:71], off offset:-3072
	s_nop 0
	global_load_dwordx2 v[146:147], v[82:83], off offset:-2560
	global_load_dwordx2 v[148:149], v[70:71], off offset:-2560
	global_load_dwordx2 v[150:151], v[82:83], off offset:-2048
	global_load_dwordx2 v[152:153], v[70:71], off offset:-2048
	s_nop 0
	s_nop 0
	global_load_dwordx2 v[154:155], v[82:83], off offset:-1536
	global_load_dwordx2 v[156:157], v[70:71], off offset:-1536
	s_nop 0
	global_load_dwordx2 v[158:159], v[82:83], off offset:-1024
	global_load_dwordx2 v[160:161], v[70:71], off offset:-1024
	global_load_dwordx2 v[162:163], v[82:83], off offset:-512
	s_nop 0
	global_load_dwordx2 v[164:165], v[70:71], off offset:-512
	s_nop 0
	s_nop 0
	global_load_dwordx2 v[166:167], v[82:83], off
	s_nop 0
	global_load_dwordx2 v[168:169], v[52:53], off offset:-4096
	s_nop 0
	global_load_dwordx2 v[170:171], v[114:115], off offset:-3584
	global_load_dwordx2 v[172:173], v[52:53], off offset:-3584
	global_load_dwordx2 v[174:175], v[114:115], off offset:-3072
	global_load_dwordx2 v[176:177], v[52:53], off offset:-3072
	s_nop 0
	s_nop 0
	global_load_dwordx2 v[178:179], v[114:115], off offset:-2560
	global_load_dwordx2 v[180:181], v[52:53], off offset:-2560
	s_nop 0
	global_load_dwordx2 v[182:183], v[114:115], off offset:-2048
	global_load_dwordx2 v[184:185], v[52:53], off offset:-2048
	global_load_dwordx2 v[186:187], v[114:115], off offset:-1536
	global_load_dwordx2 v[188:189], v[52:53], off offset:-1536
	s_nop 0
	s_nop 0
	global_load_dwordx2 v[190:191], v[114:115], off offset:-1024
	global_load_dwordx2 v[194:195], v[52:53], off offset:-1024
	s_nop 0
	global_load_dwordx2 v[196:197], v[114:115], off offset:-512
	global_load_dwordx2 v[198:199], v[52:53], off offset:-512
	global_load_dwordx2 v[200:201], v[114:115], off
	s_nop 0
	global_load_dwordx2 v[202:203], v[52:53], off
	s_movk_i32 s0, 0x1000
	s_nop 1
	s_waitcnt vmcnt(31)
	v_lshlrev_b32_e32 v58, 16, v138
	v_and_b32_e32 v59, 0xffff0000, v138
	v_lshlrev_b32_e32 v54, 16, v139
	v_and_b32_e32 v55, 0xffff0000, v139
	s_waitcnt vmcnt(30)
	v_lshlrev_b32_e32 v60, 16, v140
	v_and_b32_e32 v61, 0xffff0000, v140
	v_lshlrev_b32_e32 v56, 16, v141
	v_and_b32_e32 v57, 0xffff0000, v141
	v_pk_fma_f32 v[54:55], v[54:55], s[88:89], v[56:57] op_sel_hi:[1,0,1]
	v_pk_fma_f32 v[56:57], v[58:59], s[88:89], v[60:61] op_sel_hi:[1,0,1]
	v_mov_b32_e32 v61, v55
	v_pk_mov_b32 v[58:59], v[56:57], v[54:55] op_sel:[1,0]
	v_mov_b32_e32 v60, v56
	v_pk_add_f32 v[58:59], v[58:59], v[60:61]
	s_nop 0
	v_add_f32_e32 v58, v58, v59
	v_add_f32_e32 v72, 0, v58
	s_nop 1
	s_waitcnt vmcnt(29)
	v_lshlrev_b32_e32 v62, 16, v142
	v_and_b32_e32 v63, 0xffff0000, v142
	v_lshlrev_b32_e32 v58, 16, v143
	v_and_b32_e32 v59, 0xffff0000, v143
	s_waitcnt vmcnt(28)
	v_lshlrev_b32_e32 v64, 16, v144
	v_and_b32_e32 v65, 0xffff0000, v144
	v_lshlrev_b32_e32 v60, 16, v145
	v_and_b32_e32 v61, 0xffff0000, v145
	v_pk_fma_f32 v[60:61], v[58:59], s[88:89], v[60:61] op_sel_hi:[1,0,1]
	v_pk_fma_f32 v[58:59], v[62:63], s[88:89], v[64:65] op_sel_hi:[1,0,1]
	v_mov_b32_e32 v65, v61
	v_pk_mov_b32 v[62:63], v[58:59], v[60:61] op_sel:[1,0]
	v_mov_b32_e32 v64, v58
	v_pk_add_f32 v[62:63], v[62:63], v[64:65]
	s_nop 0
	v_pk_add_f32 v[74:75], v[62:63], v[62:63] op_sel:[0,1] op_sel_hi:[1,0]
	s_nop 1
	s_waitcnt vmcnt(27)
	v_lshlrev_b32_e32 v66, 16, v146
	v_and_b32_e32 v67, 0xffff0000, v146
	v_lshlrev_b32_e32 v62, 16, v147
	v_and_b32_e32 v63, 0xffff0000, v147
	s_waitcnt vmcnt(26)
	v_lshlrev_b32_e32 v68, 16, v148
	v_and_b32_e32 v69, 0xffff0000, v148
	v_lshlrev_b32_e32 v64, 16, v149
	v_and_b32_e32 v65, 0xffff0000, v149
	v_pk_fma_f32 v[64:65], v[62:63], s[88:89], v[64:65] op_sel_hi:[1,0,1]
	v_pk_fma_f32 v[62:63], v[66:67], s[88:89], v[68:69] op_sel_hi:[1,0,1]
	s_nop 1
	v_add_f32_e32 v76, v62, v63
	v_add_f32_e32 v78, v64, v65
	s_waitcnt vmcnt(25)
	v_lshlrev_b32_e32 v80, 16, v150
	v_and_b32_e32 v81, 0xffff0000, v150
	v_lshlrev_b32_e32 v66, 16, v151
	v_and_b32_e32 v67, 0xffff0000, v151
	s_waitcnt vmcnt(24)
	v_lshlrev_b32_e32 v84, 16, v152
	v_and_b32_e32 v85, 0xffff0000, v152
	v_lshlrev_b32_e32 v68, 16, v153
	v_and_b32_e32 v69, 0xffff0000, v153
	v_pk_fma_f32 v[68:69], v[66:67], s[88:89], v[68:69] op_sel_hi:[1,0,1]
	v_pk_fma_f32 v[66:67], v[80:81], s[88:89], v[84:85] op_sel_hi:[1,0,1]
	v_mov_b32_e32 v77, v68
	v_mov_b32_e32 v73, v66
	v_mov_b32_e32 v75, v67
	v_mov_b32_e32 v79, v69
	v_pk_add_f32 v[72:73], v[72:73], v[74:75]
	v_pk_add_f32 v[74:75], v[76:77], v[78:79]
	s_nop 0
	v_pk_add_f32 v[72:73], v[72:73], v[74:75]
	s_nop 0
	v_pk_add_f32 v[84:85], v[72:73], v[72:73] op_sel:[0,1] op_sel_hi:[1,0]
	s_nop 1
	s_waitcnt vmcnt(23)
	v_lshlrev_b32_e32 v76, 16, v154
	v_and_b32_e32 v77, 0xffff0000, v154
	v_lshlrev_b32_e32 v72, 16, v155
	v_and_b32_e32 v73, 0xffff0000, v155
	s_waitcnt vmcnt(22)
	v_lshlrev_b32_e32 v78, 16, v156
	v_and_b32_e32 v79, 0xffff0000, v156
	v_lshlrev_b32_e32 v74, 16, v157
	v_and_b32_e32 v75, 0xffff0000, v157
	v_pk_fma_f32 v[80:81], v[72:73], s[88:89], v[74:75] op_sel_hi:[1,0,1]
	v_pk_fma_f32 v[78:79], v[76:77], s[88:89], v[78:79] op_sel_hi:[1,0,1]
	v_mov_b32_e32 v75, v81
	v_pk_mov_b32 v[72:73], v[78:79], v[80:81] op_sel:[1,0]
	v_mov_b32_e32 v74, v78
	v_pk_add_f32 v[72:73], v[72:73], v[74:75]
	s_nop 0
	v_pk_add_f32 v[86:87], v[72:73], v[72:73] op_sel:[0,1] op_sel_hi:[1,0]
	s_nop 1
	s_waitcnt vmcnt(21)
; __device__ __forceinline__ float bflo(unsigned w) { return __uint_as_float(w << 16); }
; __device__ __forceinline__ float bfhi(unsigned w) { return __uint_as_float(w & 0xffff0000u); }
; __global__ void __launch_bounds__(NWAVES * 64, 2) mega_fwd(Args args) {
;     ...
;             for (int j = 0; j < 16; ++j) { const v2u xv = *(const v2u*)(xr + 4 * lane + 256 * j); const v2u m = *(const v2u*)(mr + 4 * lane + 256 * j);
;                 v[j] = (f32x4){bflo(xv[0]), bfhi(xv[0]), bflo(xv[1]), bfhi(xv[1])} * DEEP_ALPHA + (f32x4){bflo(m[0]), bfhi(m[0]), bflo(m[1]), bfhi(m[1])}; s += (v[j][0] + v[j][1]) + (v[j][2] + v[j][3]); }
	v_lshlrev_b32_e32 v88, 16, v158
	v_and_b32_e32 v89, 0xffff0000, v158
	v_lshlrev_b32_e32 v72, 16, v159
	v_and_b32_e32 v73, 0xffff0000, v159
	s_waitcnt vmcnt(20)
	v_lshlrev_b32_e32 v90, 16, v160
	v_and_b32_e32 v91, 0xffff0000, v160
	v_lshlrev_b32_e32 v74, 16, v161
	v_and_b32_e32 v75, 0xffff0000, v161
	v_pk_fma_f32 v[76:77], v[72:73], s[88:89], v[74:75] op_sel_hi:[1,0,1]
	s_nop 1
	v_pk_fma_f32 v[74:75], v[88:89], s[88:89], v[90:91] op_sel_hi:[1,0,1]
	v_add_f32_e32 v90, v76, v77
	v_add_f32_e32 v88, v74, v75
	s_waitcnt vmcnt(19)
	v_lshlrev_b32_e32 v92, 16, v162
	v_and_b32_e32 v93, 0xffff0000, v162
	v_lshlrev_b32_e32 v72, 16, v163
	v_and_b32_e32 v73, 0xffff0000, v163
	s_waitcnt vmcnt(18)
	v_lshlrev_b32_e32 v94, 16, v164
	v_and_b32_e32 v95, 0xffff0000, v164
	v_lshlrev_b32_e32 v70, 16, v165
	v_and_b32_e32 v71, 0xffff0000, v165
	v_pk_fma_f32 v[72:73], v[72:73], s[88:89], v[70:71] op_sel_hi:[1,0,1]
	v_pk_fma_f32 v[70:71], v[92:93], s[88:89], v[94:95] op_sel_hi:[1,0,1]
	v_mov_b32_e32 v89, v72
	v_mov_b32_e32 v85, v70
	v_mov_b32_e32 v87, v71
	v_mov_b32_e32 v91, v73
	v_pk_add_f32 v[84:85], v[84:85], v[86:87]
	v_pk_add_f32 v[86:87], v[88:89], v[90:91]
	s_nop 0
	v_pk_add_f32 v[84:85], v[84:85], v[86:87]
	s_nop 0
	v_pk_add_f32 v[94:95], v[84:85], v[84:85] op_sel:[0,1] op_sel_hi:[1,0]
	s_nop 1
	s_waitcnt vmcnt(17)
	v_lshlrev_b32_e32 v86, 16, v166
	v_and_b32_e32 v87, 0xffff0000, v166
	v_lshlrev_b32_e32 v82, 16, v167
	v_and_b32_e32 v83, 0xffff0000, v167
	s_waitcnt vmcnt(16)
	v_lshlrev_b32_e32 v88, 16, v168
	v_and_b32_e32 v89, 0xffff0000, v168
	v_lshlrev_b32_e32 v84, 16, v169
	v_and_b32_e32 v85, 0xffff0000, v169
	v_pk_fma_f32 v[84:85], v[82:83], s[88:89], v[84:85] op_sel_hi:[1,0,1]
	v_pk_fma_f32 v[82:83], v[86:87], s[88:89], v[88:89] op_sel_hi:[1,0,1]
	v_mov_b32_e32 v89, v85
	v_pk_mov_b32 v[86:87], v[82:83], v[84:85] op_sel:[1,0]
	v_mov_b32_e32 v88, v82
	v_pk_add_f32 v[86:87], v[86:87], v[88:89]
	s_nop 0
	v_pk_add_f32 v[96:97], v[86:87], v[86:87] op_sel:[0,1] op_sel_hi:[1,0]
	s_nop 1
	s_waitcnt vmcnt(15)
	v_lshlrev_b32_e32 v90, 16, v170
	v_and_b32_e32 v91, 0xffff0000, v170
	v_lshlrev_b32_e32 v86, 16, v171
	v_and_b32_e32 v87, 0xffff0000, v171
	s_waitcnt vmcnt(14)
	v_lshlrev_b32_e32 v92, 16, v172
	v_and_b32_e32 v93, 0xffff0000, v172
	v_lshlrev_b32_e32 v88, 16, v173
	v_and_b32_e32 v89, 0xffff0000, v173
	v_pk_fma_f32 v[88:89], v[86:87], s[88:89], v[88:89] op_sel_hi:[1,0,1]
	v_pk_fma_f32 v[86:87], v[90:91], s[88:89], v[92:93] op_sel_hi:[1,0,1]
	s_nop 1
	v_add_f32_e32 v98, v86, v87
	v_add_f32_e32 v100, v88, v89
	s_waitcnt vmcnt(13)
	v_lshlrev_b32_e32 v102, 16, v174
	v_and_b32_e32 v103, 0xffff0000, v174
	v_lshlrev_b32_e32 v90, 16, v175
	v_and_b32_e32 v91, 0xffff0000, v175
	s_waitcnt vmcnt(12)
	v_lshlrev_b32_e32 v104, 16, v176
	v_and_b32_e32 v105, 0xffff0000, v176
	v_lshlrev_b32_e32 v92, 16, v177
	v_and_b32_e32 v93, 0xffff0000, v177
	v_pk_fma_f32 v[92:93], v[90:91], s[88:89], v[92:93] op_sel_hi:[1,0,1]
	v_pk_fma_f32 v[90:91], v[102:103], s[88:89], v[104:105] op_sel_hi:[1,0,1]
	v_mov_b32_e32 v99, v92
	v_mov_b32_e32 v95, v90
	v_mov_b32_e32 v97, v91
	v_mov_b32_e32 v101, v93
	v_pk_add_f32 v[94:95], v[94:95], v[96:97]
	v_pk_add_f32 v[96:97], v[98:99], v[100:101]
	s_nop 0
	v_pk_add_f32 v[94:95], v[94:95], v[96:97]
	s_nop 0
	v_pk_add_f32 v[106:107], v[94:95], v[94:95] op_sel:[0,1] op_sel_hi:[1,0]
	s_nop 1
	s_waitcnt vmcnt(11)
	v_lshlrev_b32_e32 v98, 16, v178
	v_and_b32_e32 v99, 0xffff0000, v178
	v_lshlrev_b32_e32 v94, 16, v179
	v_and_b32_e32 v95, 0xffff0000, v179
	s_waitcnt vmcnt(10)
	v_lshlrev_b32_e32 v100, 16, v180
	v_and_b32_e32 v101, 0xffff0000, v180
	v_lshlrev_b32_e32 v96, 16, v181
	v_and_b32_e32 v97, 0xffff0000, v181
	v_pk_fma_f32 v[96:97], v[94:95], s[88:89], v[96:97] op_sel_hi:[1,0,1]
	v_pk_fma_f32 v[94:95], v[98:99], s[88:89], v[100:101] op_sel_hi:[1,0,1]
	v_mov_b32_e32 v101, v97
	v_pk_mov_b32 v[98:99], v[94:95], v[96:97] op_sel:[1,0]
	v_mov_b32_e32 v100, v94
	v_pk_add_f32 v[98:99], v[98:99], v[100:101]
	s_nop 0
	v_pk_add_f32 v[108:109], v[98:99], v[98:99] op_sel:[0,1] op_sel_hi:[1,0]
	s_nop 1
	s_waitcnt vmcnt(9)
	v_lshlrev_b32_e32 v102, 16, v182
	v_and_b32_e32 v103, 0xffff0000, v182
	v_lshlrev_b32_e32 v98, 16, v183
	v_and_b32_e32 v99, 0xffff0000, v183
	s_waitcnt vmcnt(8)
	v_lshlrev_b32_e32 v104, 16, v184
	v_and_b32_e32 v105, 0xffff0000, v184
	v_lshlrev_b32_e32 v100, 16, v185
	v_and_b32_e32 v101, 0xffff0000, v185
	v_pk_fma_f32 v[100:101], v[98:99], s[88:89], v[100:101] op_sel_hi:[1,0,1]
	v_pk_fma_f32 v[98:99], v[102:103], s[88:89], v[104:105] op_sel_hi:[1,0,1]
	s_nop 1
	v_add_f32_e32 v110, v98, v99
	v_add_f32_e32 v112, v100, v101
	s_waitcnt vmcnt(7)
	v_lshlrev_b32_e32 v116, 16, v186
	v_and_b32_e32 v117, 0xffff0000, v186
	v_lshlrev_b32_e32 v102, 16, v187
	v_and_b32_e32 v103, 0xffff0000, v187
	s_waitcnt vmcnt(6)
	v_lshlrev_b32_e32 v118, 16, v188
	v_and_b32_e32 v119, 0xffff0000, v188
	v_lshlrev_b32_e32 v104, 16, v189
	v_and_b32_e32 v105, 0xffff0000, v189
	v_pk_fma_f32 v[104:105], v[102:103], s[88:89], v[104:105] op_sel_hi:[1,0,1]
	v_pk_fma_f32 v[102:103], v[116:117], s[88:89], v[118:119] op_sel_hi:[1,0,1]
	v_mov_b32_e32 v111, v104
	v_mov_b32_e32 v107, v102
	v_mov_b32_e32 v109, v103
	v_mov_b32_e32 v113, v105
	v_pk_add_f32 v[106:107], v[106:107], v[108:109]
	v_pk_add_f32 v[108:109], v[110:111], v[112:113]
	s_nop 0
	v_pk_add_f32 v[106:107], v[106:107], v[108:109]
	s_nop 0
	v_pk_add_f32 v[118:119], v[106:107], v[106:107] op_sel:[0,1] op_sel_hi:[1,0]
	s_nop 1
	s_waitcnt vmcnt(5)
	v_lshlrev_b32_e32 v110, 16, v190
	v_and_b32_e32 v111, 0xffff0000, v190
	v_lshlrev_b32_e32 v106, 16, v191
	v_and_b32_e32 v107, 0xffff0000, v191
	s_waitcnt vmcnt(4)
; __device__ __forceinline__ float bflo(unsigned w) { return __uint_as_float(w << 16); }
; __device__ __forceinline__ float bfhi(unsigned w) { return __uint_as_float(w & 0xffff0000u); }
; __global__ void __launch_bounds__(NWAVES * 64, 2) mega_fwd(Args args) {
;     ...
;                 v[j] = (f32x4){bflo(xv[0]), bfhi(xv[0]), bflo(xv[1]), bfhi(xv[1])} * DEEP_ALPHA + (f32x4){bflo(m[0]), bfhi(m[0]), bflo(m[1]), bfhi(m[1])}; s += (v[j][0] + v[j][1]) + (v[j][2] + v[j][3]); }
;             const float mean = wave_sum(s, lane) * (1.0f / DM); float q = 0.f;
; #pragma unroll
;             for (int j = 0; j < 16; ++j) { v[j] = v[j] - mean; q += (v[j][0] * v[j][0] + v[j][1] * v[j][1]) + (v[j][2] * v[j][2] + v[j][3] * v[j][3]); }
	v_lshlrev_b32_e32 v112, 16, v194
	v_and_b32_e32 v113, 0xffff0000, v194
	v_lshlrev_b32_e32 v108, 16, v195
	v_and_b32_e32 v109, 0xffff0000, v195
	v_pk_fma_f32 v[108:109], v[106:107], s[88:89], v[108:109] op_sel_hi:[1,0,1]
	v_pk_fma_f32 v[106:107], v[110:111], s[88:89], v[112:113] op_sel_hi:[1,0,1]
	v_mov_b32_e32 v113, v109
	v_pk_mov_b32 v[110:111], v[106:107], v[108:109] op_sel:[1,0]
	v_mov_b32_e32 v112, v106
	v_pk_add_f32 v[110:111], v[110:111], v[112:113]
	s_nop 0
	v_pk_add_f32 v[120:121], v[110:111], v[110:111] op_sel:[0,1] op_sel_hi:[1,0]
	s_nop 1
	s_waitcnt vmcnt(3)
	v_lshlrev_b32_e32 v116, 16, v196
	v_and_b32_e32 v117, 0xffff0000, v196
	v_lshlrev_b32_e32 v110, 16, v197
	v_and_b32_e32 v111, 0xffff0000, v197
	s_waitcnt vmcnt(2)
	v_lshlrev_b32_e32 v122, 16, v198
	v_and_b32_e32 v123, 0xffff0000, v198
	v_lshlrev_b32_e32 v112, 16, v199
	v_and_b32_e32 v113, 0xffff0000, v199
	v_pk_fma_f32 v[112:113], v[110:111], s[88:89], v[112:113] op_sel_hi:[1,0,1]
	v_pk_fma_f32 v[110:111], v[116:117], s[88:89], v[122:123] op_sel_hi:[1,0,1]
	s_nop 1
	v_add_f32_e32 v122, v110, v111
	v_add_f32_e32 v124, v112, v113
	s_waitcnt vmcnt(1)
	v_lshlrev_b32_e32 v132, 16, v200
	v_and_b32_e32 v133, 0xffff0000, v200
	v_lshlrev_b32_e32 v114, 16, v201
	v_and_b32_e32 v115, 0xffff0000, v201
	s_waitcnt vmcnt(0)
	v_lshlrev_b32_e32 v134, 16, v202
	v_and_b32_e32 v135, 0xffff0000, v202
	v_lshlrev_b32_e32 v116, 16, v203
	v_and_b32_e32 v117, 0xffff0000, v203
	v_pk_fma_f32 v[114:115], v[114:115], s[88:89], v[116:117] op_sel_hi:[1,0,1]
	v_pk_fma_f32 v[116:117], v[132:133], s[88:89], v[134:135] op_sel_hi:[1,0,1]
	v_mov_b32_e32 v123, v114
	v_mov_b32_e32 v119, v116
	v_mov_b32_e32 v121, v117
	v_mov_b32_e32 v125, v115
	v_pk_add_f32 v[118:119], v[118:119], v[120:121]
	v_pk_add_f32 v[120:121], v[122:123], v[124:125]
	s_nop 0
	v_pk_add_f32 v[118:119], v[118:119], v[120:121]
	s_nop 0
	v_add_f32_e32 v118, v118, v119
	ds_bpermute_b32 v119, v126, v118
	s_waitcnt lgkmcnt(0)
	v_add_f32_e32 v118, v118, v119
	ds_bpermute_b32 v119, v127, v118
	s_waitcnt lgkmcnt(0)
	v_add_f32_e32 v118, v118, v119
	ds_bpermute_b32 v119, v128, v118
	s_waitcnt lgkmcnt(0)
	v_add_f32_e32 v118, v118, v119
	ds_bpermute_b32 v119, v129, v118
	s_waitcnt lgkmcnt(0)
	v_add_f32_e32 v118, v118, v119
	ds_bpermute_b32 v119, v130, v118
	s_waitcnt lgkmcnt(0)
	v_add_f32_e32 v118, v118, v119
	ds_bpermute_b32 v119, v131, v118
	s_waitcnt lgkmcnt(0)
	v_add_f32_e32 v132, v118, v119
	v_fmamk_f32 v57, v132, 0xb9800000, v57
	v_fmac_f32_e32 v56, 0xb9800000, v132
	v_fmamk_f32 v55, v132, 0xb9800000, v55
	v_fmac_f32_e32 v54, 0xb9800000, v132
	v_pk_mul_f32 v[118:119], v[54:55], v[54:55]
	v_pk_mul_f32 v[120:121], v[56:57], v[56:57]
	v_fmamk_f32 v59, v132, 0xb9800000, v59
	v_pk_mov_b32 v[122:123], v[120:121], v[118:119] op_sel:[1,0]
	v_mov_b32_e32 v121, v119
	v_fmac_f32_e32 v58, 0xb9800000, v132
	v_fmamk_f32 v61, v132, 0xb9800000, v61
	v_fmac_f32_e32 v60, 0xb9800000, v132
	v_pk_add_f32 v[118:119], v[122:123], v[120:121]
	v_pk_mul_f32 v[120:121], v[60:61], v[60:61]
	v_pk_mul_f32 v[122:123], v[58:59], v[58:59]
	v_fmamk_f32 v67, v132, 0xb9800000, v67
	v_pk_mov_b32 v[124:125], v[122:123], v[120:121] op_sel:[1,0]
	v_mov_b32_e32 v123, v121
	v_pk_add_f32 v[120:121], v[124:125], v[122:123]
	v_fmac_f32_e32 v66, 0xb9800000, v132
	v_mul_f32_e32 v122, v66, v66
	v_mul_f32_e32 v123, v67, v67
	v_pk_add_f32 v[118:119], v[118:119], v[118:119] op_sel:[0,1] op_sel_hi:[1,0]
	v_pk_add_f32 v[120:121], v[120:121], v[120:121] op_sel:[0,1] op_sel_hi:[1,0]
	v_fmamk_f32 v63, v132, 0xb9800000, v63
	v_fmamk_f32 v65, v132, 0xb9800000, v65
	v_mov_b32_e32 v119, v122
	v_mov_b32_e32 v121, v123
	v_fmac_f32_e32 v62, 0xb9800000, v132
	v_fmac_f32_e32 v64, 0xb9800000, v132
	v_fmamk_f32 v69, v132, 0xb9800000, v69
	v_fmac_f32_e32 v68, 0xb9800000, v132
	v_pk_add_f32 v[118:119], v[118:119], v[120:121]
	v_mul_f32_e32 v120, v63, v63
	v_mul_f32_e32 v122, v65, v65
	v_mul_f32_e32 v124, v68, v68
	v_mul_f32_e32 v125, v69, v69
	v_pk_fma_f32 v[120:121], v[62:63], v[62:63], v[120:121] op_sel_hi:[1,1,0]
	v_pk_fma_f32 v[122:123], v[64:65], v[64:65], v[122:123] op_sel_hi:[1,1,0]
	v_mov_b32_e32 v121, v124
	v_mov_b32_e32 v123, v125
	v_pk_add_f32 v[120:121], v[120:121], v[122:123]
	v_fmamk_f32 v79, v132, 0xb9800000, v79
	v_fmac_f32_e32 v78, 0xb9800000, v132
	v_fmamk_f32 v81, v132, 0xb9800000, v81
	v_fmac_f32_e32 v80, 0xb9800000, v132
	v_pk_add_f32 v[118:119], v[118:119], v[120:121]
	v_pk_mul_f32 v[120:121], v[80:81], v[80:81]
	v_pk_mul_f32 v[122:123], v[78:79], v[78:79]
	v_fmamk_f32 v71, v132, 0xb9800000, v71
	v_pk_mov_b32 v[124:125], v[122:123], v[120:121] op_sel:[1,0]
	v_mov_b32_e32 v123, v121
	v_pk_add_f32 v[120:121], v[124:125], v[122:123]
	v_fmac_f32_e32 v70, 0xb9800000, v132
	v_mul_f32_e32 v122, v70, v70
	v_mul_f32_e32 v123, v71, v71
	v_pk_add_f32 v[118:119], v[118:119], v[118:119] op_sel:[0,1] op_sel_hi:[1,0]
	v_pk_add_f32 v[120:121], v[120:121], v[120:121] op_sel:[0,1] op_sel_hi:[1,0]
	v_fmamk_f32 v75, v132, 0xb9800000, v75
	v_fmamk_f32 v77, v132, 0xb9800000, v77
	v_mov_b32_e32 v119, v122
	v_mov_b32_e32 v121, v123
	v_fmac_f32_e32 v74, 0xb9800000, v132
	v_fmac_f32_e32 v76, 0xb9800000, v132
	v_fmamk_f32 v73, v132, 0xb9800000, v73
	v_fmac_f32_e32 v72, 0xb9800000, v132
	v_pk_add_f32 v[118:119], v[118:119], v[120:121]
	v_mul_f32_e32 v120, v75, v75
	v_mul_f32_e32 v122, v77, v77
	v_mul_f32_e32 v124, v72, v72
	v_mul_f32_e32 v125, v73, v73
	v_pk_fma_f32 v[120:121], v[74:75], v[74:75], v[120:121] op_sel_hi:[1,1,0]
	v_pk_fma_f32 v[122:123], v[76:77], v[76:77], v[122:123] op_sel_hi:[1,1,0]
	v_mov_b32_e32 v121, v124
	v_mov_b32_e32 v123, v125
	v_pk_add_f32 v[120:121], v[120:121], v[122:123]
; __global__ void __launch_bounds__(NWAVES * 64, 2) mega_fwd(Args args) {
;     ...
;             for (int j = 0; j < 16; ++j) { v[j] = v[j] - mean; q += (v[j][0] * v[j][0] + v[j][1] * v[j][1]) + (v[j][2] * v[j][2] + v[j][3] * v[j][3]); }
;             const float rstd = 1.0f / sqrtf(wave_sum(q, lane) * (1.0f / DM) + LN_EPS);
	v_fmamk_f32 v83, v132, 0xb9800000, v83
	v_fmac_f32_e32 v82, 0xb9800000, v132
	v_fmamk_f32 v85, v132, 0xb9800000, v85
	v_fmac_f32_e32 v84, 0xb9800000, v132
	v_pk_add_f32 v[118:119], v[118:119], v[120:121]
	v_pk_mul_f32 v[120:121], v[84:85], v[84:85]
	v_pk_mul_f32 v[122:123], v[82:83], v[82:83]
	v_fmamk_f32 v91, v132, 0xb9800000, v91
	v_pk_mov_b32 v[124:125], v[122:123], v[120:121] op_sel:[1,0]
	v_mov_b32_e32 v123, v121
	v_pk_add_f32 v[120:121], v[124:125], v[122:123]
	v_fmac_f32_e32 v90, 0xb9800000, v132
	v_mul_f32_e32 v122, v90, v90
	v_mul_f32_e32 v123, v91, v91
	v_pk_add_f32 v[118:119], v[118:119], v[118:119] op_sel:[0,1] op_sel_hi:[1,0]
	v_pk_add_f32 v[120:121], v[120:121], v[120:121] op_sel:[0,1] op_sel_hi:[1,0]
	v_fmamk_f32 v87, v132, 0xb9800000, v87
	v_fmamk_f32 v89, v132, 0xb9800000, v89
	v_mov_b32_e32 v119, v122
	v_mov_b32_e32 v121, v123
	v_fmac_f32_e32 v86, 0xb9800000, v132
	v_fmac_f32_e32 v88, 0xb9800000, v132
	v_fmamk_f32 v93, v132, 0xb9800000, v93
	v_fmac_f32_e32 v92, 0xb9800000, v132
	v_pk_add_f32 v[118:119], v[118:119], v[120:121]
	v_mul_f32_e32 v120, v87, v87
	v_mul_f32_e32 v122, v89, v89
	v_mul_f32_e32 v124, v92, v92
	v_mul_f32_e32 v125, v93, v93
	v_pk_fma_f32 v[120:121], v[86:87], v[86:87], v[120:121] op_sel_hi:[1,1,0]
	v_pk_fma_f32 v[122:123], v[88:89], v[88:89], v[122:123] op_sel_hi:[1,1,0]
	v_mov_b32_e32 v121, v124
	v_mov_b32_e32 v123, v125
	v_pk_add_f32 v[120:121], v[120:121], v[122:123]
	v_fmamk_f32 v95, v132, 0xb9800000, v95
	v_fmac_f32_e32 v94, 0xb9800000, v132
	v_fmamk_f32 v97, v132, 0xb9800000, v97
	v_fmac_f32_e32 v96, 0xb9800000, v132
	v_pk_add_f32 v[118:119], v[118:119], v[120:121]
	v_pk_mul_f32 v[120:121], v[96:97], v[96:97]
	v_pk_mul_f32 v[122:123], v[94:95], v[94:95]
	v_fmamk_f32 v103, v132, 0xb9800000, v103
	v_pk_mov_b32 v[124:125], v[122:123], v[120:121] op_sel:[1,0]
	v_mov_b32_e32 v123, v121
	v_pk_add_f32 v[120:121], v[124:125], v[122:123]
	v_fmac_f32_e32 v102, 0xb9800000, v132
	v_mul_f32_e32 v122, v102, v102
	v_mul_f32_e32 v123, v103, v103
	v_pk_add_f32 v[118:119], v[118:119], v[118:119] op_sel:[0,1] op_sel_hi:[1,0]
	v_pk_add_f32 v[120:121], v[120:121], v[120:121] op_sel:[0,1] op_sel_hi:[1,0]
	v_fmamk_f32 v99, v132, 0xb9800000, v99
	v_fmamk_f32 v101, v132, 0xb9800000, v101
	v_mov_b32_e32 v119, v122
	v_mov_b32_e32 v121, v123
	v_fmac_f32_e32 v98, 0xb9800000, v132
	v_fmac_f32_e32 v100, 0xb9800000, v132
	v_fmamk_f32 v105, v132, 0xb9800000, v105
	v_fmac_f32_e32 v104, 0xb9800000, v132
	v_pk_add_f32 v[118:119], v[118:119], v[120:121]
	v_mul_f32_e32 v120, v99, v99
	v_mul_f32_e32 v122, v101, v101
	v_mul_f32_e32 v124, v104, v104
	v_mul_f32_e32 v125, v105, v105
	v_pk_fma_f32 v[120:121], v[98:99], v[98:99], v[120:121] op_sel_hi:[1,1,0]
	v_pk_fma_f32 v[122:123], v[100:101], v[100:101], v[122:123] op_sel_hi:[1,1,0]
	v_mov_b32_e32 v121, v124
	v_mov_b32_e32 v123, v125
	v_pk_add_f32 v[120:121], v[120:121], v[122:123]
	v_fmamk_f32 v107, v132, 0xb9800000, v107
	v_fmac_f32_e32 v106, 0xb9800000, v132
	v_fmamk_f32 v109, v132, 0xb9800000, v109
	v_fmac_f32_e32 v108, 0xb9800000, v132
	v_pk_add_f32 v[118:119], v[118:119], v[120:121]
	v_pk_mul_f32 v[120:121], v[108:109], v[108:109]
	v_pk_mul_f32 v[122:123], v[106:107], v[106:107]
	v_fmamk_f32 v117, v132, 0xb9800000, v117
	v_pk_mov_b32 v[124:125], v[122:123], v[120:121] op_sel:[1,0]
	v_mov_b32_e32 v123, v121
	v_pk_add_f32 v[120:121], v[124:125], v[122:123]
	v_fmac_f32_e32 v116, 0xb9800000, v132
	v_mul_f32_e32 v122, v116, v116
	v_mul_f32_e32 v123, v117, v117
	v_pk_add_f32 v[118:119], v[118:119], v[118:119] op_sel:[0,1] op_sel_hi:[1,0]
	v_pk_add_f32 v[120:121], v[120:121], v[120:121] op_sel:[0,1] op_sel_hi:[1,0]
	v_fmamk_f32 v111, v132, 0xb9800000, v111
	v_fmamk_f32 v113, v132, 0xb9800000, v113
	v_mov_b32_e32 v119, v122
	v_mov_b32_e32 v121, v123
	v_fmac_f32_e32 v110, 0xb9800000, v132
	v_fmac_f32_e32 v112, 0xb9800000, v132
	v_fmamk_f32 v115, v132, 0xb9800000, v115
	v_fmac_f32_e32 v114, 0xb9800000, v132
	v_pk_add_f32 v[118:119], v[118:119], v[120:121]
	v_mul_f32_e32 v120, v111, v111
	v_mul_f32_e32 v122, v113, v113
	v_mul_f32_e32 v124, v114, v114
	v_mul_f32_e32 v125, v115, v115
	v_pk_fma_f32 v[120:121], v[110:111], v[110:111], v[120:121] op_sel_hi:[1,1,0]
	v_pk_fma_f32 v[122:123], v[112:113], v[112:113], v[122:123] op_sel_hi:[1,1,0]
	v_mov_b32_e32 v121, v124
	v_mov_b32_e32 v123, v125
	v_pk_add_f32 v[120:121], v[120:121], v[122:123]
	s_nop 0
	v_pk_add_f32 v[118:119], v[118:119], v[120:121]
	s_nop 0
	v_add_f32_e32 v118, v118, v119
	ds_bpermute_b32 v119, v126, v118
	s_waitcnt lgkmcnt(0)
	v_add_f32_e32 v118, v118, v119
	ds_bpermute_b32 v119, v127, v118
	s_waitcnt lgkmcnt(0)
	v_add_f32_e32 v118, v118, v119
	ds_bpermute_b32 v119, v128, v118
	s_waitcnt lgkmcnt(0)
	v_add_f32_e32 v118, v118, v119
	ds_bpermute_b32 v119, v129, v118
	s_waitcnt lgkmcnt(0)
	v_add_f32_e32 v118, v118, v119
	ds_bpermute_b32 v119, v130, v118
	s_waitcnt lgkmcnt(0)
	v_add_f32_e32 v118, v118, v119
	ds_bpermute_b32 v119, v131, v118
	s_waitcnt lgkmcnt(0)
; __global__ void __launch_bounds__(NWAVES * 64, 2) mega_fwd(Args args) {
;     ...
;             const float rstd = 1.0f / sqrtf(wave_sum(q, lane) * (1.0f / DM) + LN_EPS);
; #pragma unroll
;             for (int j = 0; j < 16; ++j) { const f32x4 gg = *(const f32x4*)(ln2_g + 4 * lane + 256 * j), bb = *(const f32x4*)(ln2_b + 4 * lane + 256 * j);
;                 *(f32x4*)(yr + 4 * lane + 256 * j) = v[j] * rstd * gg + bb; }
	v_add_f32_e32 v118, v118, v119
	v_mov_b32_e32 v119, 0x3727c5ac
	v_fmamk_f32 v118, v118, 0x39800000, v119
	v_cmp_gt_f32_e32 vcc, s55, v118
	v_mul_f32_e32 v119, 0x4f800000, v118
	s_nop 0
	v_cndmask_b32_e32 v118, v118, v119, vcc
	v_sqrt_f32_e32 v119, v118
	s_nop 0
	v_add_u32_e32 v120, -1, v119
	v_fma_f32 v121, -v120, v119, v118
	v_cmp_ge_f32_e64 s[38:39], 0, v121
	v_add_u32_e32 v121, 1, v119
	s_nop 0
	v_cndmask_b32_e64 v120, v119, v120, s[38:39]
	v_fma_f32 v119, -v121, v119, v118
	v_cmp_lt_f32_e64 s[38:39], 0, v119
	s_nop 1
	v_cndmask_b32_e64 v119, v120, v121, s[38:39]
	v_mul_f32_e32 v120, 0x37800000, v119
	v_cndmask_b32_e32 v119, v119, v120, vcc
	v_cmp_class_f32_e32 vcc, v118, v216
	s_nop 1
	v_cndmask_b32_e32 v118, v119, v118, vcc
	v_div_scale_f32 v119, s[4:5], v118, v118, 1.0
	v_rcp_f32_e32 v120, v119
	v_readlane_b32 s4, v255, 30
	v_readlane_b32 s5, v255, 31
	v_fma_f32 v121, -v119, v120, 1.0
	v_fmac_f32_e32 v120, v121, v120
	v_div_scale_f32 v121, vcc, 1.0, v118, 1.0
	v_mul_f32_e32 v122, v121, v120
	v_fma_f32 v123, -v119, v122, v121
	v_fmac_f32_e32 v122, v123, v120
	v_fma_f32 v119, -v119, v122, v121
	v_div_fmas_f32 v119, v119, v120, v122
	global_load_dwordx4 v[122:125], v[0:1], off
	global_load_dwordx4 v[132:135], v[2:3], off
	v_div_fixup_f32 v118, v119, v118, 1.0
	v_pk_mul_f32 v[136:137], v[118:119], v[56:57] op_sel_hi:[0,1]
	v_pk_mul_f32 v[54:55], v[118:119], v[54:55] op_sel_hi:[0,1]
	v_lshl_add_u64 v[120:121], s[42:43], 0, v[192:193]
	v_pk_mul_f32 v[60:61], v[118:119], v[60:61] op_sel_hi:[0,1]
	v_pk_mul_f32 v[58:59], v[118:119], v[58:59] op_sel_hi:[0,1]
	v_pk_mul_f32 v[64:65], v[118:119], v[64:65] op_sel_hi:[0,1]
	v_pk_mul_f32 v[62:63], v[118:119], v[62:63] op_sel_hi:[0,1]
	s_waitcnt vmcnt(0)
	v_pk_fma_f32 v[56:57], v[124:125], v[54:55], v[134:135]
	v_pk_fma_f32 v[54:55], v[122:123], v[136:137], v[132:133]
	global_store_dwordx4 v[120:121], v[54:57], off
	global_load_dwordx4 v[54:57], v[0:1], off offset:1024
	s_nop 0
	global_load_dwordx4 v[122:125], v[2:3], off offset:1024
	s_waitcnt vmcnt(0)
	v_pk_fma_f32 v[54:55], v[54:55], v[58:59], v[122:123]
	v_pk_fma_f32 v[56:57], v[56:57], v[60:61], v[124:125]
	global_store_dwordx4 v[120:121], v[54:57], off offset:1024
	global_load_dwordx4 v[54:57], v[0:1], off offset:2048
	s_nop 0
	global_load_dwordx4 v[58:61], v[2:3], off offset:2048
	s_waitcnt vmcnt(0)
	v_pk_fma_f32 v[54:55], v[54:55], v[62:63], v[58:59]
	v_pk_fma_f32 v[56:57], v[56:57], v[64:65], v[60:61]
	global_store_dwordx4 v[120:121], v[54:57], off offset:2048
	global_load_dwordx4 v[54:57], v[0:1], off offset:3072
	s_nop 0
	global_load_dwordx4 v[58:61], v[2:3], off offset:3072
	v_pk_mul_f32 v[62:63], v[118:119], v[68:69] op_sel_hi:[0,1]
	v_pk_mul_f32 v[64:65], v[118:119], v[66:67] op_sel_hi:[0,1]
	v_pk_mul_f32 v[66:67], v[118:119], v[76:77] op_sel_hi:[0,1]
	v_pk_mul_f32 v[68:69], v[118:119], v[74:75] op_sel_hi:[0,1]
	s_waitcnt vmcnt(0)
	v_pk_fma_f32 v[54:55], v[54:55], v[64:65], v[58:59]
	v_pk_fma_f32 v[56:57], v[56:57], v[62:63], v[60:61]
	global_store_dwordx4 v[120:121], v[54:57], off offset:3072
	global_load_dwordx4 v[54:57], v[4:5], off
	s_nop 0
	global_load_dwordx4 v[58:61], v[6:7], off
	v_pk_mul_f32 v[62:63], v[118:119], v[80:81] op_sel_hi:[0,1]
	v_pk_mul_f32 v[64:65], v[118:119], v[78:79] op_sel_hi:[0,1]
	s_waitcnt vmcnt(0)
	v_pk_fma_f32 v[56:57], v[56:57], v[62:63], v[60:61]
	v_add_co_u32_e32 v62, vcc, s0, v120
	v_pk_fma_f32 v[54:55], v[54:55], v[64:65], v[58:59]
	s_nop 0
	v_addc_co_u32_e32 v63, vcc, 0, v121, vcc
	v_add_co_u32_e32 v64, vcc, s15, v120
	s_movk_i32 s0, 0x3000
	s_nop 0
	v_addc_co_u32_e32 v65, vcc, 0, v121, vcc
	global_store_dwordx4 v[64:65], v[54:57], off offset:-4096
	global_load_dwordx4 v[54:57], v[8:9], off
	s_nop 0
	global_load_dwordx4 v[58:61], v[10:11], off
	s_waitcnt vmcnt(0)
	v_pk_fma_f32 v[54:55], v[54:55], v[68:69], v[58:59]
	v_pk_fma_f32 v[56:57], v[56:57], v[66:67], v[60:61]
	global_store_dwordx4 v[62:63], v[54:57], off offset:1024
	global_load_dwordx4 v[54:57], v[12:13], off
	s_nop 0
	global_load_dwordx4 v[58:61], v[14:15], off
	v_pk_mul_f32 v[66:67], v[118:119], v[72:73] op_sel_hi:[0,1]
	v_pk_mul_f32 v[68:69], v[118:119], v[70:71] op_sel_hi:[0,1]
	s_waitcnt vmcnt(0)
	v_pk_fma_f32 v[54:55], v[54:55], v[68:69], v[58:59]
	v_pk_fma_f32 v[56:57], v[56:57], v[66:67], v[60:61]
	global_store_dwordx4 v[62:63], v[54:57], off offset:2048
	global_load_dwordx4 v[54:57], v[16:17], off
	s_nop 0
	global_load_dwordx4 v[58:61], v[18:19], off
	v_pk_mul_f32 v[66:67], v[118:119], v[84:85] op_sel_hi:[0,1]
	v_pk_mul_f32 v[68:69], v[118:119], v[82:83] op_sel_hi:[0,1]
	s_waitcnt vmcnt(0)
	v_pk_fma_f32 v[54:55], v[54:55], v[68:69], v[58:59]
	v_pk_fma_f32 v[56:57], v[56:57], v[66:67], v[60:61]
	global_store_dwordx4 v[62:63], v[54:57], off offset:3072
	global_load_dwordx4 v[54:57], v[20:21], off
	s_nop 0
	global_load_dwordx4 v[58:61], v[22:23], off
	v_pk_mul_f32 v[62:63], v[118:119], v[88:89] op_sel_hi:[0,1]
	v_pk_mul_f32 v[66:67], v[118:119], v[86:87] op_sel_hi:[0,1]
	s_waitcnt vmcnt(0)
	v_pk_fma_f32 v[54:55], v[54:55], v[66:67], v[58:59]
	v_pk_fma_f32 v[56:57], v[56:57], v[62:63], v[60:61]
	global_store_dwordx4 v[64:65], v[54:57], off
	global_load_dwordx4 v[54:57], v[24:25], off
	s_nop 0
	global_load_dwordx4 v[58:61], v[26:27], off
	v_pk_mul_f32 v[62:63], v[118:119], v[92:93] op_sel_hi:[0,1]
	v_pk_mul_f32 v[66:67], v[118:119], v[90:91] op_sel_hi:[0,1]
	s_waitcnt vmcnt(0)
	v_pk_fma_f32 v[54:55], v[54:55], v[66:67], v[58:59]
	v_pk_fma_f32 v[56:57], v[56:57], v[62:63], v[60:61]
	global_store_dwordx4 v[64:65], v[54:57], off offset:1024
	global_load_dwordx4 v[54:57], v[28:29], off
	s_nop 0
	global_load_dwordx4 v[58:61], v[30:31], off
	v_pk_mul_f32 v[62:63], v[118:119], v[96:97] op_sel_hi:[0,1]
	v_pk_mul_f32 v[66:67], v[118:119], v[94:95] op_sel_hi:[0,1]
	s_waitcnt vmcnt(0)
; __device__ __forceinline__ unsigned pk2(float lo, float hi) { return f2bf(lo) | (f2bf(hi) << 16); }
; __global__ void __launch_bounds__(NWAVES * 64, 2) mega_fwd(Args args) {
;     ...
;             for (int j = 0; j < 16; ++j) { const f32x4 gg = *(const f32x4*)(ln2_g + 4 * lane + 256 * j), bb = *(const f32x4*)(ln2_b + 4 * lane + 256 * j);
;                 *(f32x4*)(yr + 4 * lane + 256 * j) = v[j] * rstd * gg + bb; }
;             if (g == 0) {
;                 const float* xs = args.in[1] + (size_t)row * DM;
; #pragma unroll
;                 for (int jb = 0; jb < 4; ++jb) { f32x4 t[4];
; #pragma unroll
;                     for (int j = 0; j < 4; ++j) t[j] = *(const f32x4*)(xs + 4 * lane + 256 * (4 * jb + j));
; #pragma unroll
;                     for (int j = 0; j < 4; ++j) { v2u w; w.x = pk2(t[j][0], t[j][1]); w.y = pk2(t[j][2], t[j][3]); *(v2u*)(XB + (size_t)row * DM + 4 * lane + 256 * (4 * jb + j)) = w; } }
	v_pk_fma_f32 v[54:55], v[54:55], v[66:67], v[58:59]
	v_pk_fma_f32 v[56:57], v[56:57], v[62:63], v[60:61]
	global_store_dwordx4 v[64:65], v[54:57], off offset:2048
	global_load_dwordx4 v[54:57], v[32:33], off
	s_nop 0
	global_load_dwordx4 v[58:61], v[34:35], off
	v_pk_mul_f32 v[62:63], v[118:119], v[100:101] op_sel_hi:[0,1]
	v_pk_mul_f32 v[66:67], v[118:119], v[98:99] op_sel_hi:[0,1]
	s_waitcnt vmcnt(0)
	v_pk_fma_f32 v[54:55], v[54:55], v[66:67], v[58:59]
	v_pk_fma_f32 v[56:57], v[56:57], v[62:63], v[60:61]
	global_store_dwordx4 v[64:65], v[54:57], off offset:3072
	global_load_dwordx4 v[54:57], v[36:37], off
	s_nop 0
	global_load_dwordx4 v[58:61], v[38:39], off
	v_pk_mul_f32 v[62:63], v[118:119], v[104:105] op_sel_hi:[0,1]
	v_pk_mul_f32 v[64:65], v[118:119], v[102:103] op_sel_hi:[0,1]
	v_pk_mul_f32 v[66:67], v[118:119], v[106:107] op_sel_hi:[0,1]
	s_waitcnt vmcnt(0)
	v_pk_fma_f32 v[56:57], v[56:57], v[62:63], v[60:61]
	v_add_co_u32_e32 v62, vcc, s0, v120
	v_pk_fma_f32 v[54:55], v[54:55], v[64:65], v[58:59]
	s_nop 0
	v_addc_co_u32_e32 v63, vcc, 0, v121, vcc
	global_store_dwordx4 v[62:63], v[54:57], off
	global_load_dwordx4 v[54:57], v[40:41], off
	s_nop 0
	global_load_dwordx4 v[58:61], v[42:43], off
	v_pk_mul_f32 v[64:65], v[118:119], v[108:109] op_sel_hi:[0,1]
	s_andn2_b64 vcc, exec, s[4:5]
	s_waitcnt vmcnt(0)
	v_pk_fma_f32 v[54:55], v[54:55], v[66:67], v[58:59]
	v_pk_fma_f32 v[56:57], v[56:57], v[64:65], v[60:61]
	global_store_dwordx4 v[62:63], v[54:57], off offset:1024
	global_load_dwordx4 v[54:57], v[44:45], off
	s_nop 0
	global_load_dwordx4 v[58:61], v[46:47], off
	v_pk_mul_f32 v[64:65], v[118:119], v[112:113] op_sel_hi:[0,1]
	v_pk_mul_f32 v[66:67], v[118:119], v[110:111] op_sel_hi:[0,1]
	s_waitcnt vmcnt(0)
	v_pk_fma_f32 v[54:55], v[54:55], v[66:67], v[58:59]
	v_pk_fma_f32 v[56:57], v[56:57], v[64:65], v[60:61]
	global_store_dwordx4 v[62:63], v[54:57], off offset:2048
	global_load_dwordx4 v[54:57], v[48:49], off
	s_nop 0
	global_load_dwordx4 v[58:61], v[50:51], off
	v_pk_mul_f32 v[64:65], v[118:119], v[114:115] op_sel_hi:[0,1]
	v_pk_mul_f32 v[66:67], v[118:119], v[116:117] op_sel_hi:[0,1]
	s_waitcnt vmcnt(0)
	v_pk_fma_f32 v[54:55], v[54:55], v[66:67], v[58:59]
	v_pk_fma_f32 v[56:57], v[56:57], v[64:65], v[60:61]
	global_store_dwordx4 v[62:63], v[54:57], off offset:3072
	s_cbranch_vccnz .LBB0_661
	s_nop 0
	v_lshl_add_u64 v[54:55], s[40:41], 0, v[192:193]
	global_load_dwordx4 v[56:59], v[54:55], off
	global_load_dwordx4 v[60:63], v[54:55], off offset:1024
	global_load_dwordx4 v[64:67], v[54:55], off offset:2048
	global_load_dwordx4 v[68:71], v[54:55], off offset:3072
	s_mov_b32 s4, 0xdfffe200
	s_mov_b32 s5, -1
	v_lshl_add_u64 v[72:73], v[52:53], 0, s[4:5]
	s_mov_b32 s4, 0xdfffe400
	s_mov_b32 s5, -1
	v_lshl_add_u64 v[74:75], v[52:53], 0, s[4:5]
	s_mov_b32 s4, 0xdfffe600
	s_mov_b32 s5, -1
	v_lshl_add_u64 v[76:77], v[52:53], 0, s[4:5]
	s_mov_b32 s4, 0xdfffe800
	v_add_co_u32_e32 v80, vcc, s15, v54
	s_mov_b32 s5, -1
	s_nop 0
	v_addc_co_u32_e32 v81, vcc, 0, v55, vcc
	s_movk_i32 s0, 0x1000
	v_lshl_add_u64 v[78:79], v[52:53], 0, s[4:5]
	s_mov_b32 s4, 0xdfffea00
	s_mov_b32 s5, -1
	s_waitcnt vmcnt(3)
	v_bfe_u32 v82, v56, 16, 1
	v_bfe_u32 v84, v58, 16, 1
	v_bfe_u32 v83, v57, 16, 1
	v_bfe_u32 v85, v59, 16, 1
	s_waitcnt vmcnt(2)
	v_bfe_u32 v86, v60, 16, 1
	v_bfe_u32 v88, v62, 16, 1
	s_waitcnt vmcnt(1)
	v_bfe_u32 v90, v64, 16, 1
	v_bfe_u32 v92, v66, 16, 1
	s_waitcnt vmcnt(0)
	v_bfe_u32 v94, v68, 16, 1
	v_bfe_u32 v96, v70, 16, 1
	v_add3_u32 v56, v56, v82, s33
	v_add3_u32 v58, v58, v84, s33
	v_bfe_u32 v87, v61, 16, 1
	v_bfe_u32 v89, v63, 16, 1
	v_bfe_u32 v91, v65, 16, 1
	v_bfe_u32 v93, v67, 16, 1
	v_bfe_u32 v95, v69, 16, 1
	v_bfe_u32 v97, v71, 16, 1
	v_add3_u32 v57, v57, v83, s33
	v_add3_u32 v59, v59, v85, s33
	v_add3_u32 v60, v60, v86, s33
	v_add3_u32 v62, v62, v88, s33
	v_add3_u32 v64, v64, v90, s33
	v_add3_u32 v66, v66, v92, s33
	v_add3_u32 v68, v68, v94, s33
	v_add3_u32 v70, v70, v96, s33
	v_lshrrev_b32_e32 v56, 16, v56
	v_lshrrev_b32_e32 v58, 16, v58
	v_add3_u32 v61, v61, v87, s33
	v_add3_u32 v63, v63, v89, s33
	v_add3_u32 v65, v65, v91, s33
	v_add3_u32 v67, v67, v93, s33
	v_add3_u32 v69, v69, v95, s33
	v_add3_u32 v71, v71, v97, s33
	v_lshrrev_b32_e32 v60, 16, v60
	v_lshrrev_b32_e32 v62, 16, v62
	v_lshrrev_b32_e32 v64, 16, v64
	v_lshrrev_b32_e32 v66, 16, v66
	v_lshrrev_b32_e32 v68, 16, v68
	v_lshrrev_b32_e32 v70, 16, v70
	v_and_or_b32 v56, v57, s54, v56
	v_and_or_b32 v57, v59, s54, v58
	v_and_or_b32 v58, v61, s54, v60
	v_and_or_b32 v59, v63, s54, v62
	v_and_or_b32 v60, v65, s54, v64
	v_and_or_b32 v61, v67, s54, v66
	v_and_or_b32 v62, v69, s54, v68
	v_and_or_b32 v63, v71, s54, v70
	global_store_dwordx2 v[72:73], v[56:57], off
	global_store_dwordx2 v[74:75], v[58:59], off
	global_store_dwordx2 v[76:77], v[60:61], off
	global_store_dwordx2 v[78:79], v[62:63], off
	v_add_co_u32_e32 v68, vcc, s0, v54
	global_load_dwordx4 v[56:59], v[80:81], off offset:-4096
	s_nop 0
	v_addc_co_u32_e32 v69, vcc, 0, v55, vcc
	global_load_dwordx4 v[60:63], v[68:69], off offset:1024
	global_load_dwordx4 v[64:67], v[68:69], off offset:2048
	s_nop 0
	global_load_dwordx4 v[68:71], v[68:69], off offset:3072
	v_lshl_add_u64 v[72:73], v[52:53], 0, s[4:5]
	s_mov_b32 s4, 0xdfffec00
	s_mov_b32 s5, -1
	v_lshl_add_u64 v[74:75], v[52:53], 0, s[4:5]
	s_mov_b32 s4, 0xdfffee00
	s_mov_b32 s5, -1
	v_lshl_add_u64 v[76:77], v[52:53], 0, s[4:5]
	s_mov_b32 s4, 0xdffff000
	s_mov_b32 s5, -1
	v_lshl_add_u64 v[78:79], v[52:53], 0, s[4:5]
	s_mov_b32 s4, 0xdffff200
	s_mov_b32 s5, -1
	s_movk_i32 s0, 0x3000
	s_waitcnt vmcnt(3)
	v_bfe_u32 v82, v56, 16, 1
	v_bfe_u32 v84, v58, 16, 1
	v_bfe_u32 v83, v57, 16, 1
	v_bfe_u32 v85, v59, 16, 1
	s_waitcnt vmcnt(2)
; __device__ __forceinline__ unsigned pk2(float lo, float hi) { return f2bf(lo) | (f2bf(hi) << 16); }
; __global__ void __launch_bounds__(NWAVES * 64, 2) mega_fwd(Args args) {
;     ...
;             if (g == 0) {
;                 const float* xs = args.in[1] + (size_t)row * DM;
; #pragma unroll
;                 for (int jb = 0; jb < 4; ++jb) { f32x4 t[4];
; #pragma unroll
;                     for (int j = 0; j < 4; ++j) t[j] = *(const f32x4*)(xs + 4 * lane + 256 * (4 * jb + j));
; #pragma unroll
;                     for (int j = 0; j < 4; ++j) { v2u w; w.x = pk2(t[j][0], t[j][1]); w.y = pk2(t[j][2], t[j][3]); *(v2u*)(XB + (size_t)row * DM + 4 * lane + 256 * (4 * jb + j)) = w; } }
	v_bfe_u32 v86, v60, 16, 1
	v_bfe_u32 v88, v62, 16, 1
	s_waitcnt vmcnt(1)
	v_bfe_u32 v90, v64, 16, 1
	v_bfe_u32 v92, v66, 16, 1
	s_waitcnt vmcnt(0)
	v_bfe_u32 v94, v68, 16, 1
	v_bfe_u32 v96, v70, 16, 1
	v_add3_u32 v56, v56, v82, s33
	v_add3_u32 v58, v58, v84, s33
	v_bfe_u32 v87, v61, 16, 1
	v_bfe_u32 v89, v63, 16, 1
	v_bfe_u32 v91, v65, 16, 1
	v_bfe_u32 v93, v67, 16, 1
	v_bfe_u32 v95, v69, 16, 1
	v_bfe_u32 v97, v71, 16, 1
	v_add3_u32 v57, v57, v83, s33
	v_add3_u32 v59, v59, v85, s33
	v_add3_u32 v60, v60, v86, s33
	v_add3_u32 v62, v62, v88, s33
	v_add3_u32 v64, v64, v90, s33
	v_add3_u32 v66, v66, v92, s33
	v_add3_u32 v68, v68, v94, s33
	v_add3_u32 v70, v70, v96, s33
	v_lshrrev_b32_e32 v56, 16, v56
	v_lshrrev_b32_e32 v58, 16, v58
	v_add3_u32 v61, v61, v87, s33
	v_add3_u32 v63, v63, v89, s33
	v_add3_u32 v65, v65, v91, s33
	v_add3_u32 v67, v67, v93, s33
	v_add3_u32 v69, v69, v95, s33
	v_add3_u32 v71, v71, v97, s33
	v_lshrrev_b32_e32 v60, 16, v60
	v_lshrrev_b32_e32 v62, 16, v62
	v_lshrrev_b32_e32 v64, 16, v64
	v_lshrrev_b32_e32 v66, 16, v66
	v_lshrrev_b32_e32 v68, 16, v68
	v_lshrrev_b32_e32 v70, 16, v70
	v_and_or_b32 v56, v57, s54, v56
	v_and_or_b32 v57, v59, s54, v58
	v_and_or_b32 v58, v61, s54, v60
	v_and_or_b32 v59, v63, s54, v62
	v_and_or_b32 v60, v65, s54, v64
	v_and_or_b32 v61, v67, s54, v66
	v_and_or_b32 v62, v69, s54, v68
	v_and_or_b32 v63, v71, s54, v70
	global_store_dwordx2 v[72:73], v[56:57], off
	global_store_dwordx2 v[74:75], v[58:59], off
	global_store_dwordx2 v[76:77], v[60:61], off
	global_store_dwordx2 v[78:79], v[62:63], off
	global_load_dwordx4 v[56:59], v[80:81], off
	s_nop 0
	global_load_dwordx4 v[60:63], v[80:81], off offset:1024
	global_load_dwordx4 v[64:67], v[80:81], off offset:2048
	global_load_dwordx4 v[68:71], v[80:81], off offset:3072
	v_lshl_add_u64 v[72:73], v[52:53], 0, s[4:5]
	s_mov_b32 s4, 0xdffff400
	s_mov_b32 s5, -1
	v_lshl_add_u64 v[74:75], v[52:53], 0, s[4:5]
	s_mov_b32 s4, 0xdffff600
	v_add_co_u32_e32 v80, vcc, s0, v54
	s_mov_b32 s5, -1
	s_nop 0
	v_addc_co_u32_e32 v81, vcc, 0, v55, vcc
	v_lshl_add_u64 v[76:77], v[52:53], 0, s[4:5]
	s_mov_b32 s4, 0xdffff800
	s_mov_b32 s5, -1
	v_lshl_add_u64 v[78:79], v[52:53], 0, s[4:5]
	s_mov_b32 s4, 0xdffffa00
	s_mov_b32 s5, -1
	s_waitcnt vmcnt(3)
	v_bfe_u32 v54, v56, 16, 1
	v_bfe_u32 v82, v58, 16, 1
	v_bfe_u32 v55, v57, 16, 1
	v_bfe_u32 v83, v59, 16, 1
	s_waitcnt vmcnt(2)
	v_bfe_u32 v84, v60, 16, 1
	v_bfe_u32 v86, v62, 16, 1
	s_waitcnt vmcnt(1)
	v_bfe_u32 v88, v64, 16, 1
	v_bfe_u32 v90, v66, 16, 1
	s_waitcnt vmcnt(0)
	v_bfe_u32 v92, v68, 16, 1
	v_bfe_u32 v94, v70, 16, 1
	v_add3_u32 v54, v56, v54, s33
	v_add3_u32 v56, v58, v82, s33
	v_bfe_u32 v85, v61, 16, 1
	v_bfe_u32 v87, v63, 16, 1
	v_bfe_u32 v89, v65, 16, 1
	v_bfe_u32 v91, v67, 16, 1
	v_bfe_u32 v93, v69, 16, 1
	v_bfe_u32 v95, v71, 16, 1
	v_add3_u32 v55, v57, v55, s33
	v_add3_u32 v57, v59, v83, s33
	v_add3_u32 v58, v60, v84, s33
	v_add3_u32 v60, v62, v86, s33
	v_add3_u32 v62, v64, v88, s33
	v_add3_u32 v64, v66, v90, s33
	v_add3_u32 v66, v68, v92, s33
	v_add3_u32 v68, v70, v94, s33
	v_lshrrev_b32_e32 v54, 16, v54
	v_lshrrev_b32_e32 v56, 16, v56
	v_add3_u32 v59, v61, v85, s33
	v_add3_u32 v61, v63, v87, s33
	v_add3_u32 v63, v65, v89, s33
	v_add3_u32 v65, v67, v91, s33
	v_add3_u32 v67, v69, v93, s33
	v_add3_u32 v69, v71, v95, s33
	v_lshrrev_b32_e32 v58, 16, v58
	v_lshrrev_b32_e32 v60, 16, v60
	v_lshrrev_b32_e32 v62, 16, v62
	v_lshrrev_b32_e32 v64, 16, v64
	v_lshrrev_b32_e32 v66, 16, v66
	v_lshrrev_b32_e32 v68, 16, v68
	v_and_or_b32 v54, v55, s54, v54
	v_and_or_b32 v55, v57, s54, v56
	v_and_or_b32 v56, v59, s54, v58
	v_and_or_b32 v57, v61, s54, v60
	v_and_or_b32 v58, v63, s54, v62
	v_and_or_b32 v59, v65, s54, v64
	v_and_or_b32 v60, v67, s54, v66
	v_and_or_b32 v61, v69, s54, v68
	global_store_dwordx2 v[72:73], v[54:55], off
	global_store_dwordx2 v[74:75], v[56:57], off
	global_store_dwordx2 v[76:77], v[58:59], off
	global_store_dwordx2 v[78:79], v[60:61], off
	global_load_dwordx4 v[54:57], v[80:81], off
	s_nop 0
	global_load_dwordx4 v[58:61], v[80:81], off offset:1024
	global_load_dwordx4 v[62:65], v[80:81], off offset:2048
	global_load_dwordx4 v[66:69], v[80:81], off offset:3072
	v_lshl_add_u64 v[70:71], v[52:53], 0, s[4:5]
	s_mov_b32 s4, 0xdffffc00
	s_mov_b32 s5, -1
	v_lshl_add_u64 v[72:73], v[52:53], 0, s[4:5]
	s_mov_b32 s4, 0xdffffe00
	s_mov_b32 s5, -1
	v_lshl_add_u64 v[74:75], v[52:53], 0, s[4:5]
	s_brev_b32 s4, 7
	s_mov_b32 s5, -1
	v_lshl_add_u64 v[76:77], v[52:53], 0, s[4:5]
	s_waitcnt vmcnt(3)
	v_bfe_u32 v78, v54, 16, 1
	v_bfe_u32 v80, v56, 16, 1
	v_bfe_u32 v79, v55, 16, 1
	v_bfe_u32 v81, v57, 16, 1
	s_waitcnt vmcnt(2)
	v_bfe_u32 v82, v58, 16, 1
	v_bfe_u32 v84, v60, 16, 1
	s_waitcnt vmcnt(1)
	v_bfe_u32 v86, v62, 16, 1
	v_bfe_u32 v88, v64, 16, 1
	s_waitcnt vmcnt(0)
	v_bfe_u32 v90, v66, 16, 1
	v_bfe_u32 v92, v68, 16, 1
	v_add3_u32 v54, v54, v78, s33
	v_add3_u32 v56, v56, v80, s33
	v_bfe_u32 v83, v59, 16, 1
	v_bfe_u32 v85, v61, 16, 1
	v_bfe_u32 v87, v63, 16, 1
	v_bfe_u32 v89, v65, 16, 1
	v_bfe_u32 v91, v67, 16, 1
	v_bfe_u32 v93, v69, 16, 1
	v_add3_u32 v55, v55, v79, s33
	v_add3_u32 v57, v57, v81, s33
	v_add3_u32 v58, v58, v82, s33
	v_add3_u32 v60, v60, v84, s33
	v_add3_u32 v62, v62, v86, s33
	v_add3_u32 v64, v64, v88, s33
	v_add3_u32 v66, v66, v90, s33
	v_add3_u32 v68, v68, v92, s33
	v_lshrrev_b32_e32 v54, 16, v54
	v_lshrrev_b32_e32 v56, 16, v56
	v_add3_u32 v59, v59, v83, s33
	v_add3_u32 v61, v61, v85, s33
	v_add3_u32 v63, v63, v87, s33
	v_add3_u32 v65, v65, v89, s33
	v_add3_u32 v67, v67, v91, s33
	v_add3_u32 v69, v69, v93, s33
	v_lshrrev_b32_e32 v58, 16, v58
	v_lshrrev_b32_e32 v60, 16, v60
	v_lshrrev_b32_e32 v62, 16, v62
	v_lshrrev_b32_e32 v64, 16, v64
	v_lshrrev_b32_e32 v66, 16, v66
	v_lshrrev_b32_e32 v68, 16, v68
	v_and_or_b32 v54, v55, s54, v54
	v_and_or_b32 v55, v57, s54, v56
	v_and_or_b32 v56, v59, s54, v58
	v_and_or_b32 v57, v61, s54, v60
	v_and_or_b32 v58, v63, s54, v62
	v_and_or_b32 v59, v65, s54, v64
	v_and_or_b32 v60, v67, s54, v66
	v_and_or_b32 v61, v69, s54, v68
	global_store_dwordx2 v[70:71], v[54:55], off
	global_store_dwordx2 v[72:73], v[56:57], off
	global_store_dwordx2 v[74:75], v[58:59], off
	global_store_dwordx2 v[76:77], v[60:61], off
	s_branch .LBB0_661
